# DN chunk-local forward substitution rewritten by hand: Ls row reads software-pipelined 10 deep, two rows interleaved, 64 rhs loads in flight, cvt_pk stores
# speedup vs baseline: 1.2311x; 1.0040x over previous
; NI void dn_chunk_local(const P& p, int dh, int n, char* lds) {
;     ...
;   {
;     const int col = tid;
;     float x[64];
;     const float* src = CQ + (size_t)row0 * 1536 + hd * 128 + (col < 128 ? 1024 + col : 512 + (col - 128));
; #pragma unroll
;     for (int hb = 0; hb < 2; ++hb) {
; #pragma unroll
;       for (int i = hb * 32; i < hb * 32 + 32; ++i) {
;         const float f = (col < 128) ? bS[i] : bS[i] * egS[i];
;         x[i] = src[(long)i * rstride] * f;
.LBB0_281:
	s_or_b64 exec, exec, s[10:11]
	v_mul_f32_e32 v0, v3, v35
	v_mul_f32_e32 v0, v0, v6
	v_cmp_gt_i32_e32 vcc, v50, v7
	s_mul_i32 s18, s26, 0x600
	s_mul_i32 s10, s25, 0x1800
	v_cndmask_b32_e32 v0, 0, v0, vcc
	s_ashr_i32 s19, s18, 31
	ds_write_b32 v32, v0 offset:16956
	v_mul_f32_e32 v0, v1, v6
	s_ashr_i32 s11, s10, 31
	v_bfe_u32 v1, v0, 16, 1
	s_add_u32 s10, s30, s10
	v_add3_u32 v0, v0, v1, s61
	s_addc_u32 s11, s31, s11
	s_lshl_b32 s74, s1, 2
	s_movk_i32 s1, 0x80
	global_store_short_d16_hi v[38:39], v0, off offset:30
	v_cmp_gt_i32_e64 s[22:23], s1, v4
	v_mov_b32_e32 v0, 0x180
	s_add_u32 s10, s10, s74
	v_cndmask_b32_e64 v0, v0, v236, s[22:23]
	v_add_u32_e32 v0, v0, v4
	s_addc_u32 s11, s11, 0
	v_ashrrev_i32_e32 v1, 31, v0
	v_lshl_add_u64 v[6:7], v[0:1], 2, s[10:11]
	s_waitcnt lgkmcnt(0)
	s_barrier
	s_lshl_b64 s[10:11], s[18:19], 2
	global_load_dword v8, v[6:7], off
	v_lshl_add_u64 v[6:7], v[6:7], 0, s[10:11]
	global_load_dword v9, v[6:7], off
	v_lshl_add_u64 v[6:7], v[6:7], 0, s[10:11]
	global_load_dword v10, v[6:7], off
	v_lshl_add_u64 v[6:7], v[6:7], 0, s[10:11]
	global_load_dword v11, v[6:7], off
	v_lshl_add_u64 v[6:7], v[6:7], 0, s[10:11]
	global_load_dword v12, v[6:7], off
	v_lshl_add_u64 v[6:7], v[6:7], 0, s[10:11]
	global_load_dword v13, v[6:7], off
	v_lshl_add_u64 v[6:7], v[6:7], 0, s[10:11]
	global_load_dword v14, v[6:7], off
	v_lshl_add_u64 v[6:7], v[6:7], 0, s[10:11]
	global_load_dword v15, v[6:7], off
	v_lshl_add_u64 v[6:7], v[6:7], 0, s[10:11]
	global_load_dword v16, v[6:7], off
	v_lshl_add_u64 v[6:7], v[6:7], 0, s[10:11]
	global_load_dword v17, v[6:7], off
	v_lshl_add_u64 v[6:7], v[6:7], 0, s[10:11]
	global_load_dword v18, v[6:7], off
	v_lshl_add_u64 v[6:7], v[6:7], 0, s[10:11]
	global_load_dword v19, v[6:7], off
	v_lshl_add_u64 v[6:7], v[6:7], 0, s[10:11]
	global_load_dword v20, v[6:7], off
	v_lshl_add_u64 v[6:7], v[6:7], 0, s[10:11]
	global_load_dword v21, v[6:7], off
	v_lshl_add_u64 v[6:7], v[6:7], 0, s[10:11]
	global_load_dword v22, v[6:7], off
	v_lshl_add_u64 v[6:7], v[6:7], 0, s[10:11]
	global_load_dword v23, v[6:7], off
	v_lshl_add_u64 v[6:7], v[6:7], 0, s[10:11]
	global_load_dword v24, v[6:7], off
	v_lshl_add_u64 v[6:7], v[6:7], 0, s[10:11]
	global_load_dword v25, v[6:7], off
	v_lshl_add_u64 v[6:7], v[6:7], 0, s[10:11]
	global_load_dword v26, v[6:7], off
	v_lshl_add_u64 v[6:7], v[6:7], 0, s[10:11]
	global_load_dword v27, v[6:7], off
	v_lshl_add_u64 v[6:7], v[6:7], 0, s[10:11]
	global_load_dword v28, v[6:7], off
	v_lshl_add_u64 v[6:7], v[6:7], 0, s[10:11]
	global_load_dword v29, v[6:7], off
	v_lshl_add_u64 v[6:7], v[6:7], 0, s[10:11]
	global_load_dword v30, v[6:7], off
	v_lshl_add_u64 v[6:7], v[6:7], 0, s[10:11]
	global_load_dword v31, v[6:7], off
	v_lshl_add_u64 v[6:7], v[6:7], 0, s[10:11]
	global_load_dword v32, v[6:7], off
	v_lshl_add_u64 v[6:7], v[6:7], 0, s[10:11]
	global_load_dword v33, v[6:7], off
	v_lshl_add_u64 v[6:7], v[6:7], 0, s[10:11]
	global_load_dword v34, v[6:7], off
	v_lshl_add_u64 v[6:7], v[6:7], 0, s[10:11]
	global_load_dword v35, v[6:7], off
	v_lshl_add_u64 v[6:7], v[6:7], 0, s[10:11]
	global_load_dword v36, v[6:7], off
	v_lshl_add_u64 v[6:7], v[6:7], 0, s[10:11]
	global_load_dword v37, v[6:7], off
	v_lshl_add_u64 v[6:7], v[6:7], 0, s[10:11]
	global_load_dword v38, v[6:7], off
	v_lshl_add_u64 v[6:7], v[6:7], 0, s[10:11]
	global_load_dword v39, v[6:7], off
	v_lshl_add_u64 v[6:7], v[6:7], 0, s[10:11]
	global_load_dword v52, v[6:7], off
	v_lshl_add_u64 v[6:7], v[6:7], 0, s[10:11]
	global_load_dword v53, v[6:7], off
	v_lshl_add_u64 v[6:7], v[6:7], 0, s[10:11]
	global_load_dword v54, v[6:7], off
	v_lshl_add_u64 v[6:7], v[6:7], 0, s[10:11]
	global_load_dword v55, v[6:7], off
	v_lshl_add_u64 v[6:7], v[6:7], 0, s[10:11]
	global_load_dword v56, v[6:7], off
	v_lshl_add_u64 v[6:7], v[6:7], 0, s[10:11]
	global_load_dword v57, v[6:7], off
	v_lshl_add_u64 v[6:7], v[6:7], 0, s[10:11]
	global_load_dword v58, v[6:7], off
	v_lshl_add_u64 v[6:7], v[6:7], 0, s[10:11]
	global_load_dword v59, v[6:7], off
	v_lshl_add_u64 v[6:7], v[6:7], 0, s[10:11]
	global_load_dword v60, v[6:7], off
	v_lshl_add_u64 v[6:7], v[6:7], 0, s[10:11]
	global_load_dword v61, v[6:7], off
	v_lshl_add_u64 v[6:7], v[6:7], 0, s[10:11]
	global_load_dword v62, v[6:7], off
	v_lshl_add_u64 v[6:7], v[6:7], 0, s[10:11]
	global_load_dword v63, v[6:7], off
	v_lshl_add_u64 v[6:7], v[6:7], 0, s[10:11]
	global_load_dword v64, v[6:7], off
	v_lshl_add_u64 v[6:7], v[6:7], 0, s[10:11]
	global_load_dword v65, v[6:7], off
	v_lshl_add_u64 v[6:7], v[6:7], 0, s[10:11]
	global_load_dword v66, v[6:7], off
	v_lshl_add_u64 v[6:7], v[6:7], 0, s[10:11]
	global_load_dword v67, v[6:7], off
	v_lshl_add_u64 v[6:7], v[6:7], 0, s[10:11]
	global_load_dword v68, v[6:7], off
	v_lshl_add_u64 v[6:7], v[6:7], 0, s[10:11]
	global_load_dword v69, v[6:7], off
	v_lshl_add_u64 v[6:7], v[6:7], 0, s[10:11]
	global_load_dword v70, v[6:7], off
	v_lshl_add_u64 v[6:7], v[6:7], 0, s[10:11]
	global_load_dword v71, v[6:7], off
	v_lshl_add_u64 v[6:7], v[6:7], 0, s[10:11]
	global_load_dword v72, v[6:7], off
	v_lshl_add_u64 v[6:7], v[6:7], 0, s[10:11]
	global_load_dword v73, v[6:7], off
	v_lshl_add_u64 v[6:7], v[6:7], 0, s[10:11]
	global_load_dword v74, v[6:7], off
	v_lshl_add_u64 v[6:7], v[6:7], 0, s[10:11]
	global_load_dword v75, v[6:7], off
	v_lshl_add_u64 v[6:7], v[6:7], 0, s[10:11]
	global_load_dword v76, v[6:7], off
	v_lshl_add_u64 v[6:7], v[6:7], 0, s[10:11]
	global_load_dword v77, v[6:7], off
	v_lshl_add_u64 v[6:7], v[6:7], 0, s[10:11]
	global_load_dword v78, v[6:7], off
	v_lshl_add_u64 v[6:7], v[6:7], 0, s[10:11]
	global_load_dword v79, v[6:7], off
	v_lshl_add_u64 v[6:7], v[6:7], 0, s[10:11]
	global_load_dword v80, v[6:7], off
	v_lshl_add_u64 v[6:7], v[6:7], 0, s[10:11]
	global_load_dword v81, v[6:7], off
	v_lshl_add_u64 v[6:7], v[6:7], 0, s[10:11]
	global_load_dword v82, v[6:7], off
	v_lshl_add_u64 v[6:7], v[6:7], 0, s[10:11]
	global_load_dword v83, v[6:7], off
	ds_read_b128 v[84:87], v97 offset:33536
	ds_read_b128 v[102:105], v97 offset:33792
	ds_read_b128 v[88:91], v97 offset:33552
	ds_read_b128 v[106:109], v97 offset:33808
	ds_read_b128 v[92:95], v97 offset:33568
	ds_read_b128 v[110:113], v97 offset:33824
	ds_read_b128 v[98:101], v97 offset:33584
	ds_read_b128 v[114:117], v97 offset:33840
	s_waitcnt lgkmcnt(6)
; NI void dn_chunk_local(const P& p, int dh, int n, char* lds) {
;     ...
;     for (int hb = 0; hb < 2; ++hb) {
; #pragma unroll
;       for (int i = hb * 32; i < hb * 32 + 32; ++i) {
;         const float f = (col < 128) ? bS[i] : bS[i] * egS[i];
;         x[i] = src[(long)i * rstride] * f;
	v_mul_f32_e32 v102, v84, v102
	v_cndmask_b32_e64 v102, v102, v84, s[22:23]
	s_waitcnt vmcnt(63)
	v_mul_f32_e32 v8, v8, v102
	v_mul_f32_e32 v103, v85, v103
	v_cndmask_b32_e64 v103, v103, v85, s[22:23]
	s_waitcnt vmcnt(62)
	v_mul_f32_e32 v9, v9, v103
	v_mul_f32_e32 v104, v86, v104
	v_cndmask_b32_e64 v104, v104, v86, s[22:23]
	s_waitcnt vmcnt(61)
	v_mul_f32_e32 v10, v10, v104
	v_mul_f32_e32 v105, v87, v105
	v_cndmask_b32_e64 v105, v105, v87, s[22:23]
	s_waitcnt vmcnt(60)
	v_mul_f32_e32 v11, v11, v105
	s_waitcnt lgkmcnt(4)
	v_mul_f32_e32 v106, v88, v106
	v_cndmask_b32_e64 v106, v106, v88, s[22:23]
	s_waitcnt vmcnt(59)
	v_mul_f32_e32 v12, v12, v106
	v_mul_f32_e32 v107, v89, v107
	v_cndmask_b32_e64 v107, v107, v89, s[22:23]
	s_waitcnt vmcnt(58)
	v_mul_f32_e32 v13, v13, v107
	v_mul_f32_e32 v108, v90, v108
	v_cndmask_b32_e64 v108, v108, v90, s[22:23]
	s_waitcnt vmcnt(57)
	v_mul_f32_e32 v14, v14, v108
	v_mul_f32_e32 v109, v91, v109
	v_cndmask_b32_e64 v109, v109, v91, s[22:23]
	s_waitcnt vmcnt(56)
	v_mul_f32_e32 v15, v15, v109
	s_waitcnt lgkmcnt(2)
	v_mul_f32_e32 v110, v92, v110
	v_cndmask_b32_e64 v110, v110, v92, s[22:23]
	s_waitcnt vmcnt(55)
	v_mul_f32_e32 v16, v16, v110
	v_mul_f32_e32 v111, v93, v111
	v_cndmask_b32_e64 v111, v111, v93, s[22:23]
	s_waitcnt vmcnt(54)
	v_mul_f32_e32 v17, v17, v111
	v_mul_f32_e32 v112, v94, v112
	v_cndmask_b32_e64 v112, v112, v94, s[22:23]
	s_waitcnt vmcnt(53)
	v_mul_f32_e32 v18, v18, v112
	v_mul_f32_e32 v113, v95, v113
	v_cndmask_b32_e64 v113, v113, v95, s[22:23]
	s_waitcnt vmcnt(52)
	v_mul_f32_e32 v19, v19, v113
	s_waitcnt lgkmcnt(0)
	v_mul_f32_e32 v114, v98, v114
	v_cndmask_b32_e64 v114, v114, v98, s[22:23]
	s_waitcnt vmcnt(51)
	v_mul_f32_e32 v20, v20, v114
	v_mul_f32_e32 v115, v99, v115
	v_cndmask_b32_e64 v115, v115, v99, s[22:23]
	s_waitcnt vmcnt(50)
	v_mul_f32_e32 v21, v21, v115
	v_mul_f32_e32 v116, v100, v116
	v_cndmask_b32_e64 v116, v116, v100, s[22:23]
	s_waitcnt vmcnt(49)
	v_mul_f32_e32 v22, v22, v116
	v_mul_f32_e32 v117, v101, v117
	v_cndmask_b32_e64 v117, v117, v101, s[22:23]
	s_waitcnt vmcnt(48)
	v_mul_f32_e32 v23, v23, v117
	ds_read_b128 v[84:87], v97 offset:33600
	ds_read_b128 v[102:105], v97 offset:33856
	ds_read_b128 v[88:91], v97 offset:33616
	ds_read_b128 v[106:109], v97 offset:33872
	ds_read_b128 v[92:95], v97 offset:33632
	ds_read_b128 v[110:113], v97 offset:33888
	ds_read_b128 v[98:101], v97 offset:33648
	ds_read_b128 v[114:117], v97 offset:33904
	s_waitcnt lgkmcnt(6)
	v_mul_f32_e32 v102, v84, v102
	v_cndmask_b32_e64 v102, v102, v84, s[22:23]
	s_waitcnt vmcnt(47)
	v_mul_f32_e32 v24, v24, v102
	v_mul_f32_e32 v103, v85, v103
	v_cndmask_b32_e64 v103, v103, v85, s[22:23]
	s_waitcnt vmcnt(46)
	v_mul_f32_e32 v25, v25, v103
	v_mul_f32_e32 v104, v86, v104
	v_cndmask_b32_e64 v104, v104, v86, s[22:23]
	s_waitcnt vmcnt(45)
	v_mul_f32_e32 v26, v26, v104
	v_mul_f32_e32 v105, v87, v105
	v_cndmask_b32_e64 v105, v105, v87, s[22:23]
	s_waitcnt vmcnt(44)
	v_mul_f32_e32 v27, v27, v105
	s_waitcnt lgkmcnt(4)
	v_mul_f32_e32 v106, v88, v106
	v_cndmask_b32_e64 v106, v106, v88, s[22:23]
	s_waitcnt vmcnt(43)
	v_mul_f32_e32 v28, v28, v106
	v_mul_f32_e32 v107, v89, v107
	v_cndmask_b32_e64 v107, v107, v89, s[22:23]
	s_waitcnt vmcnt(42)
	v_mul_f32_e32 v29, v29, v107
	v_mul_f32_e32 v108, v90, v108
	v_cndmask_b32_e64 v108, v108, v90, s[22:23]
	s_waitcnt vmcnt(41)
	v_mul_f32_e32 v30, v30, v108
	v_mul_f32_e32 v109, v91, v109
	v_cndmask_b32_e64 v109, v109, v91, s[22:23]
	s_waitcnt vmcnt(40)
	v_mul_f32_e32 v31, v31, v109
	s_waitcnt lgkmcnt(2)
	v_mul_f32_e32 v110, v92, v110
	v_cndmask_b32_e64 v110, v110, v92, s[22:23]
	s_waitcnt vmcnt(39)
	v_mul_f32_e32 v32, v32, v110
	v_mul_f32_e32 v111, v93, v111
	v_cndmask_b32_e64 v111, v111, v93, s[22:23]
	s_waitcnt vmcnt(38)
	v_mul_f32_e32 v33, v33, v111
	v_mul_f32_e32 v112, v94, v112
	v_cndmask_b32_e64 v112, v112, v94, s[22:23]
	s_waitcnt vmcnt(37)
	v_mul_f32_e32 v34, v34, v112
	v_mul_f32_e32 v113, v95, v113
	v_cndmask_b32_e64 v113, v113, v95, s[22:23]
	s_waitcnt vmcnt(36)
	v_mul_f32_e32 v35, v35, v113
	s_waitcnt lgkmcnt(0)
	v_mul_f32_e32 v114, v98, v114
	v_cndmask_b32_e64 v114, v114, v98, s[22:23]
	s_waitcnt vmcnt(35)
	v_mul_f32_e32 v36, v36, v114
	v_mul_f32_e32 v115, v99, v115
	v_cndmask_b32_e64 v115, v115, v99, s[22:23]
	s_waitcnt vmcnt(34)
	v_mul_f32_e32 v37, v37, v115
	v_mul_f32_e32 v116, v100, v116
	v_cndmask_b32_e64 v116, v116, v100, s[22:23]
	s_waitcnt vmcnt(33)
	v_mul_f32_e32 v38, v38, v116
	v_mul_f32_e32 v117, v101, v117
	v_cndmask_b32_e64 v117, v117, v101, s[22:23]
	s_waitcnt vmcnt(32)
	v_mul_f32_e32 v39, v39, v117
	ds_read_b128 v[84:87], v97 offset:33664
	ds_read_b128 v[102:105], v97 offset:33920
	ds_read_b128 v[88:91], v97 offset:33680
	ds_read_b128 v[106:109], v97 offset:33936
	ds_read_b128 v[92:95], v97 offset:33696
	ds_read_b128 v[110:113], v97 offset:33952
	ds_read_b128 v[98:101], v97 offset:33712
	ds_read_b128 v[114:117], v97 offset:33968
	s_waitcnt lgkmcnt(6)
	v_mul_f32_e32 v102, v84, v102
	v_cndmask_b32_e64 v102, v102, v84, s[22:23]
	s_waitcnt vmcnt(31)
	v_mul_f32_e32 v52, v52, v102
	v_mul_f32_e32 v103, v85, v103
	v_cndmask_b32_e64 v103, v103, v85, s[22:23]
	s_waitcnt vmcnt(30)
	v_mul_f32_e32 v53, v53, v103
	v_mul_f32_e32 v104, v86, v104
	v_cndmask_b32_e64 v104, v104, v86, s[22:23]
	s_waitcnt vmcnt(29)
	v_mul_f32_e32 v54, v54, v104
	v_mul_f32_e32 v105, v87, v105
	v_cndmask_b32_e64 v105, v105, v87, s[22:23]
	s_waitcnt vmcnt(28)
	v_mul_f32_e32 v55, v55, v105
	s_waitcnt lgkmcnt(4)
	v_mul_f32_e32 v106, v88, v106
	v_cndmask_b32_e64 v106, v106, v88, s[22:23]
	s_waitcnt vmcnt(27)
	v_mul_f32_e32 v56, v56, v106
	v_mul_f32_e32 v107, v89, v107
	v_cndmask_b32_e64 v107, v107, v89, s[22:23]
	s_waitcnt vmcnt(26)
; NI void dn_chunk_local(const P& p, int dh, int n, char* lds) {
;     ...
;     for (int hb = 0; hb < 2; ++hb) {
; #pragma unroll
;       for (int i = hb * 32; i < hb * 32 + 32; ++i) {
;         const float f = (col < 128) ? bS[i] : bS[i] * egS[i];
;         x[i] = src[(long)i * rstride] * f;
;     ...
;       for (int i = hb * 32; i < hb * 32 + 32; ++i) {
;         float a = x[i];
; #pragma unroll
;         for (int j = 0; j < i; ++j) a -= Ls[i * 64 + j] * x[j];
;         x[i] = a;
;         if ((i & 3) == 3) __builtin_amdgcn_sched_barrier(0);
;       }
	v_mul_f32_e32 v57, v57, v107
	v_mul_f32_e32 v108, v90, v108
	v_cndmask_b32_e64 v108, v108, v90, s[22:23]
	s_waitcnt vmcnt(25)
	v_mul_f32_e32 v58, v58, v108
	v_mul_f32_e32 v109, v91, v109
	v_cndmask_b32_e64 v109, v109, v91, s[22:23]
	s_waitcnt vmcnt(24)
	v_mul_f32_e32 v59, v59, v109
	s_waitcnt lgkmcnt(2)
	v_mul_f32_e32 v110, v92, v110
	v_cndmask_b32_e64 v110, v110, v92, s[22:23]
	s_waitcnt vmcnt(23)
	v_mul_f32_e32 v60, v60, v110
	v_mul_f32_e32 v111, v93, v111
	v_cndmask_b32_e64 v111, v111, v93, s[22:23]
	s_waitcnt vmcnt(22)
	v_mul_f32_e32 v61, v61, v111
	v_mul_f32_e32 v112, v94, v112
	v_cndmask_b32_e64 v112, v112, v94, s[22:23]
	s_waitcnt vmcnt(21)
	v_mul_f32_e32 v62, v62, v112
	v_mul_f32_e32 v113, v95, v113
	v_cndmask_b32_e64 v113, v113, v95, s[22:23]
	s_waitcnt vmcnt(20)
	v_mul_f32_e32 v63, v63, v113
	s_waitcnt lgkmcnt(0)
	v_mul_f32_e32 v114, v98, v114
	v_cndmask_b32_e64 v114, v114, v98, s[22:23]
	s_waitcnt vmcnt(19)
	v_mul_f32_e32 v64, v64, v114
	v_mul_f32_e32 v115, v99, v115
	v_cndmask_b32_e64 v115, v115, v99, s[22:23]
	s_waitcnt vmcnt(18)
	v_mul_f32_e32 v65, v65, v115
	v_mul_f32_e32 v116, v100, v116
	v_cndmask_b32_e64 v116, v116, v100, s[22:23]
	s_waitcnt vmcnt(17)
	v_mul_f32_e32 v66, v66, v116
	v_mul_f32_e32 v117, v101, v117
	v_cndmask_b32_e64 v117, v117, v101, s[22:23]
	s_waitcnt vmcnt(16)
	v_mul_f32_e32 v67, v67, v117
	ds_read_b128 v[84:87], v97 offset:33728
	ds_read_b128 v[102:105], v97 offset:33984
	ds_read_b128 v[88:91], v97 offset:33744
	ds_read_b128 v[106:109], v97 offset:34000
	ds_read_b128 v[92:95], v97 offset:33760
	ds_read_b128 v[110:113], v97 offset:34016
	ds_read_b128 v[98:101], v97 offset:33776
	ds_read_b128 v[114:117], v97 offset:34032
	s_waitcnt lgkmcnt(6)
	v_mul_f32_e32 v102, v84, v102
	v_cndmask_b32_e64 v102, v102, v84, s[22:23]
	s_waitcnt vmcnt(15)
	v_mul_f32_e32 v68, v68, v102
	v_mul_f32_e32 v103, v85, v103
	v_cndmask_b32_e64 v103, v103, v85, s[22:23]
	s_waitcnt vmcnt(14)
	v_mul_f32_e32 v69, v69, v103
	v_mul_f32_e32 v104, v86, v104
	v_cndmask_b32_e64 v104, v104, v86, s[22:23]
	s_waitcnt vmcnt(13)
	v_mul_f32_e32 v70, v70, v104
	v_mul_f32_e32 v105, v87, v105
	v_cndmask_b32_e64 v105, v105, v87, s[22:23]
	s_waitcnt vmcnt(12)
	v_mul_f32_e32 v71, v71, v105
	s_waitcnt lgkmcnt(4)
	v_mul_f32_e32 v106, v88, v106
	v_cndmask_b32_e64 v106, v106, v88, s[22:23]
	s_waitcnt vmcnt(11)
	v_mul_f32_e32 v72, v72, v106
	v_mul_f32_e32 v107, v89, v107
	v_cndmask_b32_e64 v107, v107, v89, s[22:23]
	s_waitcnt vmcnt(10)
	v_mul_f32_e32 v73, v73, v107
	v_mul_f32_e32 v108, v90, v108
	v_cndmask_b32_e64 v108, v108, v90, s[22:23]
	s_waitcnt vmcnt(9)
	v_mul_f32_e32 v74, v74, v108
	v_mul_f32_e32 v109, v91, v109
	v_cndmask_b32_e64 v109, v109, v91, s[22:23]
	s_waitcnt vmcnt(8)
	v_mul_f32_e32 v75, v75, v109
	s_waitcnt lgkmcnt(2)
	v_mul_f32_e32 v110, v92, v110
	v_cndmask_b32_e64 v110, v110, v92, s[22:23]
	s_waitcnt vmcnt(7)
	v_mul_f32_e32 v76, v76, v110
	v_mul_f32_e32 v111, v93, v111
	v_cndmask_b32_e64 v111, v111, v93, s[22:23]
	s_waitcnt vmcnt(6)
	v_mul_f32_e32 v77, v77, v111
	v_mul_f32_e32 v112, v94, v112
	v_cndmask_b32_e64 v112, v112, v94, s[22:23]
	s_waitcnt vmcnt(5)
	v_mul_f32_e32 v78, v78, v112
	v_mul_f32_e32 v113, v95, v113
	v_cndmask_b32_e64 v113, v113, v95, s[22:23]
	s_waitcnt vmcnt(4)
	v_mul_f32_e32 v79, v79, v113
	s_waitcnt lgkmcnt(0)
	v_mul_f32_e32 v114, v98, v114
	v_cndmask_b32_e64 v114, v114, v98, s[22:23]
	s_waitcnt vmcnt(3)
	v_mul_f32_e32 v80, v80, v114
	v_mul_f32_e32 v115, v99, v115
	v_cndmask_b32_e64 v115, v115, v99, s[22:23]
	s_waitcnt vmcnt(2)
	v_mul_f32_e32 v81, v81, v115
	v_mul_f32_e32 v116, v100, v116
	v_cndmask_b32_e64 v116, v116, v100, s[22:23]
	s_waitcnt vmcnt(1)
	v_mul_f32_e32 v82, v82, v116
	v_mul_f32_e32 v117, v101, v117
	v_cndmask_b32_e64 v117, v117, v101, s[22:23]
	s_waitcnt vmcnt(0)
	v_mul_f32_e32 v83, v83, v117
	ds_read_b128 v[84:87], v97 offset:17152
	ds_read_b128 v[88:91], v97 offset:17408
	ds_read_b128 v[92:95], v97 offset:17664
	ds_read_b128 v[98:101], v97 offset:17920
	ds_read_b128 v[102:105], v97 offset:18176
	ds_read_b128 v[106:109], v97 offset:18432
	ds_read_b128 v[110:113], v97 offset:18192
	ds_read_b128 v[114:117], v97 offset:18448
	ds_read_b128 v[42:45], v97 offset:18688
	ds_read_b128 v[46:49], v97 offset:18944
	s_waitcnt lgkmcnt(8)
	v_fma_f32 v9, -v8, v84, v9
	v_fma_f32 v10, -v8, v88, v10
	v_fma_f32 v10, -v9, v89, v10
	ds_read_b128 v[84:87], v97 offset:18704
	ds_read_b128 v[88:91], v97 offset:18960
	s_waitcnt lgkmcnt(8)
	v_fma_f32 v11, -v8, v92, v11
	v_fma_f32 v12, -v8, v98, v12
	v_fma_f32 v11, -v9, v93, v11
	v_fma_f32 v12, -v9, v99, v12
	v_fma_f32 v11, -v10, v94, v11
	v_fma_f32 v12, -v10, v100, v12
	v_fma_f32 v12, -v11, v101, v12
	ds_read_b128 v[92:95], v97 offset:19200
	ds_read_b128 v[98:101], v97 offset:19456
	s_waitcnt lgkmcnt(8)
	v_fma_f32 v13, -v8, v102, v13
	v_fma_f32 v14, -v8, v106, v14
	v_fma_f32 v13, -v9, v103, v13
	v_fma_f32 v14, -v9, v107, v14
	v_fma_f32 v13, -v10, v104, v13
	v_fma_f32 v14, -v10, v108, v14
	v_fma_f32 v13, -v11, v105, v13
	v_fma_f32 v14, -v11, v109, v14
	ds_read_b128 v[102:105], v97 offset:19216
	ds_read_b128 v[106:109], v97 offset:19472
	s_waitcnt lgkmcnt(8)
	v_fma_f32 v13, -v12, v110, v13
	v_fma_f32 v14, -v12, v114, v14
	v_fma_f32 v14, -v13, v115, v14
	ds_read_b128 v[110:113], v97 offset:19232
	ds_read_b128 v[114:117], v97 offset:19488
	s_waitcnt lgkmcnt(8)
	v_fma_f32 v15, -v8, v42, v15
	v_fma_f32 v16, -v8, v46, v16
	v_fma_f32 v15, -v9, v43, v15
	v_fma_f32 v16, -v9, v47, v16
	v_fma_f32 v15, -v10, v44, v15
	v_fma_f32 v16, -v10, v48, v16
	v_fma_f32 v15, -v11, v45, v15
	v_fma_f32 v16, -v11, v49, v16
	ds_read_b128 v[42:45], v97 offset:19712
	ds_read_b128 v[46:49], v97 offset:19968
	s_waitcnt lgkmcnt(8)
; NI void dn_chunk_local(const P& p, int dh, int n, char* lds) {
;     ...
;       for (int i = hb * 32; i < hb * 32 + 32; ++i) {
;         float a = x[i];
; #pragma unroll
;         for (int j = 0; j < i; ++j) a -= Ls[i * 64 + j] * x[j];
;         x[i] = a;
;         if ((i & 3) == 3) __builtin_amdgcn_sched_barrier(0);
;       }
	v_fma_f32 v15, -v12, v84, v15
	v_fma_f32 v16, -v12, v88, v16
	v_fma_f32 v15, -v13, v85, v15
	v_fma_f32 v16, -v13, v89, v16
	v_fma_f32 v15, -v14, v86, v15
	v_fma_f32 v16, -v14, v90, v16
	v_fma_f32 v16, -v15, v91, v16
	ds_read_b128 v[84:87], v97 offset:19728
	ds_read_b128 v[88:91], v97 offset:19984
	s_waitcnt lgkmcnt(8)
	v_fma_f32 v17, -v8, v92, v17
	v_fma_f32 v18, -v8, v98, v18
	v_fma_f32 v17, -v9, v93, v17
	v_fma_f32 v18, -v9, v99, v18
	v_fma_f32 v17, -v10, v94, v17
	v_fma_f32 v18, -v10, v100, v18
	v_fma_f32 v17, -v11, v95, v17
	v_fma_f32 v18, -v11, v101, v18
	ds_read_b128 v[92:95], v97 offset:19744
	ds_read_b128 v[98:101], v97 offset:20000
	s_waitcnt lgkmcnt(8)
	v_fma_f32 v17, -v12, v102, v17
	v_fma_f32 v18, -v12, v106, v18
	v_fma_f32 v17, -v13, v103, v17
	v_fma_f32 v18, -v13, v107, v18
	v_fma_f32 v17, -v14, v104, v17
	v_fma_f32 v18, -v14, v108, v18
	v_fma_f32 v17, -v15, v105, v17
	v_fma_f32 v18, -v15, v109, v18
	ds_read_b128 v[102:105], v97 offset:20224
	ds_read_b128 v[106:109], v97 offset:20480
	s_waitcnt lgkmcnt(8)
	v_fma_f32 v17, -v16, v110, v17
	v_fma_f32 v18, -v16, v114, v18
	v_fma_f32 v18, -v17, v115, v18
	ds_read_b128 v[110:113], v97 offset:20240
	ds_read_b128 v[114:117], v97 offset:20496
	s_waitcnt lgkmcnt(8)
	v_fma_f32 v19, -v8, v42, v19
	v_fma_f32 v20, -v8, v46, v20
	v_fma_f32 v19, -v9, v43, v19
	v_fma_f32 v20, -v9, v47, v20
	v_fma_f32 v19, -v10, v44, v19
	v_fma_f32 v20, -v10, v48, v20
	v_fma_f32 v19, -v11, v45, v19
	v_fma_f32 v20, -v11, v49, v20
	ds_read_b128 v[42:45], v97 offset:20256
	ds_read_b128 v[46:49], v97 offset:20512
	s_waitcnt lgkmcnt(8)
	v_fma_f32 v19, -v12, v84, v19
	v_fma_f32 v20, -v12, v88, v20
	v_fma_f32 v19, -v13, v85, v19
	v_fma_f32 v20, -v13, v89, v20
	v_fma_f32 v19, -v14, v86, v19
	v_fma_f32 v20, -v14, v90, v20
	v_fma_f32 v19, -v15, v87, v19
	v_fma_f32 v20, -v15, v91, v20
	ds_read_b128 v[84:87], v97 offset:20272
	ds_read_b128 v[88:91], v97 offset:20528
	s_waitcnt lgkmcnt(8)
	v_fma_f32 v19, -v16, v92, v19
	v_fma_f32 v20, -v16, v98, v20
	v_fma_f32 v19, -v17, v93, v19
	v_fma_f32 v20, -v17, v99, v20
	v_fma_f32 v19, -v18, v94, v19
	v_fma_f32 v20, -v18, v100, v20
	v_fma_f32 v20, -v19, v101, v20
	ds_read_b128 v[92:95], v97 offset:20736
	ds_read_b128 v[98:101], v97 offset:20992
	s_waitcnt lgkmcnt(8)
	v_fma_f32 v21, -v8, v102, v21
	v_fma_f32 v22, -v8, v106, v22
	v_fma_f32 v21, -v9, v103, v21
	v_fma_f32 v22, -v9, v107, v22
	v_fma_f32 v21, -v10, v104, v21
	v_fma_f32 v22, -v10, v108, v22
	v_fma_f32 v21, -v11, v105, v21
	v_fma_f32 v22, -v11, v109, v22
	ds_read_b128 v[102:105], v97 offset:20752
	ds_read_b128 v[106:109], v97 offset:21008
	s_waitcnt lgkmcnt(8)
	v_fma_f32 v21, -v12, v110, v21
	v_fma_f32 v22, -v12, v114, v22
	v_fma_f32 v21, -v13, v111, v21
	v_fma_f32 v22, -v13, v115, v22
	v_fma_f32 v21, -v14, v112, v21
	v_fma_f32 v22, -v14, v116, v22
	v_fma_f32 v21, -v15, v113, v21
	v_fma_f32 v22, -v15, v117, v22
	ds_read_b128 v[110:113], v97 offset:20768
	ds_read_b128 v[114:117], v97 offset:21024
	s_waitcnt lgkmcnt(8)
	v_fma_f32 v21, -v16, v42, v21
	v_fma_f32 v22, -v16, v46, v22
	v_fma_f32 v21, -v17, v43, v21
	v_fma_f32 v22, -v17, v47, v22
	v_fma_f32 v21, -v18, v44, v21
	v_fma_f32 v22, -v18, v48, v22
	v_fma_f32 v21, -v19, v45, v21
	v_fma_f32 v22, -v19, v49, v22
	ds_read_b128 v[42:45], v97 offset:20784
	ds_read_b128 v[46:49], v97 offset:21040
	s_waitcnt lgkmcnt(8)
	v_fma_f32 v21, -v20, v84, v21
	v_fma_f32 v22, -v20, v88, v22
	v_fma_f32 v22, -v21, v89, v22
	ds_read_b128 v[84:87], v97 offset:21248
	ds_read_b128 v[88:91], v97 offset:21504
	s_waitcnt lgkmcnt(8)
	v_fma_f32 v23, -v8, v92, v23
	v_fma_f32 v24, -v8, v98, v24
	v_fma_f32 v23, -v9, v93, v23
	v_fma_f32 v24, -v9, v99, v24
	v_fma_f32 v23, -v10, v94, v23
	v_fma_f32 v24, -v10, v100, v24
	v_fma_f32 v23, -v11, v95, v23
	v_fma_f32 v24, -v11, v101, v24
	ds_read_b128 v[92:95], v97 offset:21264
	ds_read_b128 v[98:101], v97 offset:21520
	s_waitcnt lgkmcnt(8)
	v_fma_f32 v23, -v12, v102, v23
	v_fma_f32 v24, -v12, v106, v24
	v_fma_f32 v23, -v13, v103, v23
	v_fma_f32 v24, -v13, v107, v24
	v_fma_f32 v23, -v14, v104, v23
	v_fma_f32 v24, -v14, v108, v24
	v_fma_f32 v23, -v15, v105, v23
	v_fma_f32 v24, -v15, v109, v24
	ds_read_b128 v[102:105], v97 offset:21280
	ds_read_b128 v[106:109], v97 offset:21536
	s_waitcnt lgkmcnt(8)
	v_fma_f32 v23, -v16, v110, v23
	v_fma_f32 v24, -v16, v114, v24
	v_fma_f32 v23, -v17, v111, v23
	v_fma_f32 v24, -v17, v115, v24
	v_fma_f32 v23, -v18, v112, v23
	v_fma_f32 v24, -v18, v116, v24
	v_fma_f32 v23, -v19, v113, v23
	v_fma_f32 v24, -v19, v117, v24
	ds_read_b128 v[110:113], v97 offset:21296
	ds_read_b128 v[114:117], v97 offset:21552
	s_waitcnt lgkmcnt(8)
	v_fma_f32 v23, -v20, v42, v23
	v_fma_f32 v24, -v20, v46, v24
	v_fma_f32 v23, -v21, v43, v23
	v_fma_f32 v24, -v21, v47, v24
	v_fma_f32 v23, -v22, v44, v23
	v_fma_f32 v24, -v22, v48, v24
	v_fma_f32 v24, -v23, v49, v24
	ds_read_b128 v[42:45], v97 offset:21312
	ds_read_b128 v[46:49], v97 offset:21568
	s_waitcnt lgkmcnt(8)
	v_fma_f32 v25, -v8, v84, v25
	v_fma_f32 v26, -v8, v88, v26
	v_fma_f32 v25, -v9, v85, v25
	v_fma_f32 v26, -v9, v89, v26
	v_fma_f32 v25, -v10, v86, v25
	v_fma_f32 v26, -v10, v90, v26
	v_fma_f32 v25, -v11, v87, v25
	v_fma_f32 v26, -v11, v91, v26
	ds_read_b128 v[84:87], v97 offset:21760
	ds_read_b128 v[88:91], v97 offset:22016
	s_waitcnt lgkmcnt(8)
	v_fma_f32 v25, -v12, v92, v25
	v_fma_f32 v26, -v12, v98, v26
	v_fma_f32 v25, -v13, v93, v25
	v_fma_f32 v26, -v13, v99, v26
	v_fma_f32 v25, -v14, v94, v25
	v_fma_f32 v26, -v14, v100, v26
	v_fma_f32 v25, -v15, v95, v25
	v_fma_f32 v26, -v15, v101, v26
	ds_read_b128 v[92:95], v97 offset:21776
	ds_read_b128 v[98:101], v97 offset:22032
	s_waitcnt lgkmcnt(8)
; NI void dn_chunk_local(const P& p, int dh, int n, char* lds) {
;     ...
;       for (int i = hb * 32; i < hb * 32 + 32; ++i) {
;         float a = x[i];
; #pragma unroll
;         for (int j = 0; j < i; ++j) a -= Ls[i * 64 + j] * x[j];
;         x[i] = a;
;         if ((i & 3) == 3) __builtin_amdgcn_sched_barrier(0);
;       }
	v_fma_f32 v25, -v16, v102, v25
	v_fma_f32 v26, -v16, v106, v26
	v_fma_f32 v25, -v17, v103, v25
	v_fma_f32 v26, -v17, v107, v26
	v_fma_f32 v25, -v18, v104, v25
	v_fma_f32 v26, -v18, v108, v26
	v_fma_f32 v25, -v19, v105, v25
	v_fma_f32 v26, -v19, v109, v26
	ds_read_b128 v[102:105], v97 offset:21792
	ds_read_b128 v[106:109], v97 offset:22048
	s_waitcnt lgkmcnt(8)
	v_fma_f32 v25, -v20, v110, v25
	v_fma_f32 v26, -v20, v114, v26
	v_fma_f32 v25, -v21, v111, v25
	v_fma_f32 v26, -v21, v115, v26
	v_fma_f32 v25, -v22, v112, v25
	v_fma_f32 v26, -v22, v116, v26
	v_fma_f32 v25, -v23, v113, v25
	v_fma_f32 v26, -v23, v117, v26
	ds_read_b128 v[110:113], v97 offset:21808
	ds_read_b128 v[114:117], v97 offset:22064
	s_waitcnt lgkmcnt(8)
	v_fma_f32 v25, -v24, v42, v25
	v_fma_f32 v26, -v24, v46, v26
	v_fma_f32 v26, -v25, v47, v26
	ds_read_b128 v[42:45], v97 offset:21824
	ds_read_b128 v[46:49], v97 offset:22080
	s_waitcnt lgkmcnt(8)
	v_fma_f32 v27, -v8, v84, v27
	v_fma_f32 v28, -v8, v88, v28
	v_fma_f32 v27, -v9, v85, v27
	v_fma_f32 v28, -v9, v89, v28
	v_fma_f32 v27, -v10, v86, v27
	v_fma_f32 v28, -v10, v90, v28
	v_fma_f32 v27, -v11, v87, v27
	v_fma_f32 v28, -v11, v91, v28
	ds_read_b128 v[84:87], v97 offset:22272
	ds_read_b128 v[88:91], v97 offset:22528
	s_waitcnt lgkmcnt(8)
	v_fma_f32 v27, -v12, v92, v27
	v_fma_f32 v28, -v12, v98, v28
	v_fma_f32 v27, -v13, v93, v27
	v_fma_f32 v28, -v13, v99, v28
	v_fma_f32 v27, -v14, v94, v27
	v_fma_f32 v28, -v14, v100, v28
	v_fma_f32 v27, -v15, v95, v27
	v_fma_f32 v28, -v15, v101, v28
	ds_read_b128 v[92:95], v97 offset:22288
	ds_read_b128 v[98:101], v97 offset:22544
	s_waitcnt lgkmcnt(8)
	v_fma_f32 v27, -v16, v102, v27
	v_fma_f32 v28, -v16, v106, v28
	v_fma_f32 v27, -v17, v103, v27
	v_fma_f32 v28, -v17, v107, v28
	v_fma_f32 v27, -v18, v104, v27
	v_fma_f32 v28, -v18, v108, v28
	v_fma_f32 v27, -v19, v105, v27
	v_fma_f32 v28, -v19, v109, v28
	ds_read_b128 v[102:105], v97 offset:22304
	ds_read_b128 v[106:109], v97 offset:22560
	s_waitcnt lgkmcnt(8)
	v_fma_f32 v27, -v20, v110, v27
	v_fma_f32 v28, -v20, v114, v28
	v_fma_f32 v27, -v21, v111, v27
	v_fma_f32 v28, -v21, v115, v28
	v_fma_f32 v27, -v22, v112, v27
	v_fma_f32 v28, -v22, v116, v28
	v_fma_f32 v27, -v23, v113, v27
	v_fma_f32 v28, -v23, v117, v28
	ds_read_b128 v[110:113], v97 offset:22320
	ds_read_b128 v[114:117], v97 offset:22576
	s_waitcnt lgkmcnt(8)
	v_fma_f32 v27, -v24, v42, v27
	v_fma_f32 v28, -v24, v46, v28
	v_fma_f32 v27, -v25, v43, v27
	v_fma_f32 v28, -v25, v47, v28
	v_fma_f32 v27, -v26, v44, v27
	v_fma_f32 v28, -v26, v48, v28
	v_fma_f32 v28, -v27, v49, v28
	ds_read_b128 v[42:45], v97 offset:22336
	ds_read_b128 v[46:49], v97 offset:22592
	s_waitcnt lgkmcnt(8)
	v_fma_f32 v29, -v8, v84, v29
	v_fma_f32 v30, -v8, v88, v30
	v_fma_f32 v29, -v9, v85, v29
	v_fma_f32 v30, -v9, v89, v30
	v_fma_f32 v29, -v10, v86, v29
	v_fma_f32 v30, -v10, v90, v30
	v_fma_f32 v29, -v11, v87, v29
	v_fma_f32 v30, -v11, v91, v30
	ds_read_b128 v[84:87], v97 offset:22352
	ds_read_b128 v[88:91], v97 offset:22608
	s_waitcnt lgkmcnt(8)
	v_fma_f32 v29, -v12, v92, v29
	v_fma_f32 v30, -v12, v98, v30
	v_fma_f32 v29, -v13, v93, v29
	v_fma_f32 v30, -v13, v99, v30
	v_fma_f32 v29, -v14, v94, v29
	v_fma_f32 v30, -v14, v100, v30
	v_fma_f32 v29, -v15, v95, v29
	v_fma_f32 v30, -v15, v101, v30
	ds_read_b128 v[92:95], v97 offset:22784
	ds_read_b128 v[98:101], v97 offset:23040
	s_waitcnt lgkmcnt(8)
	v_fma_f32 v29, -v16, v102, v29
	v_fma_f32 v30, -v16, v106, v30
	v_fma_f32 v29, -v17, v103, v29
	v_fma_f32 v30, -v17, v107, v30
	v_fma_f32 v29, -v18, v104, v29
	v_fma_f32 v30, -v18, v108, v30
	v_fma_f32 v29, -v19, v105, v29
	v_fma_f32 v30, -v19, v109, v30
	ds_read_b128 v[102:105], v97 offset:22800
	ds_read_b128 v[106:109], v97 offset:23056
	s_waitcnt lgkmcnt(8)
	v_fma_f32 v29, -v20, v110, v29
	v_fma_f32 v30, -v20, v114, v30
	v_fma_f32 v29, -v21, v111, v29
	v_fma_f32 v30, -v21, v115, v30
	v_fma_f32 v29, -v22, v112, v29
	v_fma_f32 v30, -v22, v116, v30
	v_fma_f32 v29, -v23, v113, v29
	v_fma_f32 v30, -v23, v117, v30
	ds_read_b128 v[110:113], v97 offset:22816
	ds_read_b128 v[114:117], v97 offset:23072
	s_waitcnt lgkmcnt(8)
	v_fma_f32 v29, -v24, v42, v29
	v_fma_f32 v30, -v24, v46, v30
	v_fma_f32 v29, -v25, v43, v29
	v_fma_f32 v30, -v25, v47, v30
	v_fma_f32 v29, -v26, v44, v29
	v_fma_f32 v30, -v26, v48, v30
	v_fma_f32 v29, -v27, v45, v29
	v_fma_f32 v30, -v27, v49, v30
	ds_read_b128 v[42:45], v97 offset:22832
	ds_read_b128 v[46:49], v97 offset:23088
	s_waitcnt lgkmcnt(8)
	v_fma_f32 v29, -v28, v84, v29
	v_fma_f32 v30, -v28, v88, v30
	v_fma_f32 v30, -v29, v89, v30
	ds_read_b128 v[84:87], v97 offset:22848
	ds_read_b128 v[88:91], v97 offset:23104
	s_waitcnt lgkmcnt(8)
	v_fma_f32 v31, -v8, v92, v31
	v_fma_f32 v32, -v8, v98, v32
	v_fma_f32 v31, -v9, v93, v31
	v_fma_f32 v32, -v9, v99, v32
	v_fma_f32 v31, -v10, v94, v31
	v_fma_f32 v32, -v10, v100, v32
	v_fma_f32 v31, -v11, v95, v31
	v_fma_f32 v32, -v11, v101, v32
	ds_read_b128 v[92:95], v97 offset:22864
	ds_read_b128 v[98:101], v97 offset:23120
	s_waitcnt lgkmcnt(8)
	v_fma_f32 v31, -v12, v102, v31
	v_fma_f32 v32, -v12, v106, v32
	v_fma_f32 v31, -v13, v103, v31
	v_fma_f32 v32, -v13, v107, v32
	v_fma_f32 v31, -v14, v104, v31
	v_fma_f32 v32, -v14, v108, v32
	v_fma_f32 v31, -v15, v105, v31
	v_fma_f32 v32, -v15, v109, v32
	ds_read_b128 v[102:105], v97 offset:23296
	ds_read_b128 v[106:109], v97 offset:23552
	s_waitcnt lgkmcnt(8)
	v_fma_f32 v31, -v16, v110, v31
	v_fma_f32 v32, -v16, v114, v32
	v_fma_f32 v31, -v17, v111, v31
	v_fma_f32 v32, -v17, v115, v32
	v_fma_f32 v31, -v18, v112, v31
	v_fma_f32 v32, -v18, v116, v32
	v_fma_f32 v31, -v19, v113, v31
	v_fma_f32 v32, -v19, v117, v32
	ds_read_b128 v[110:113], v97 offset:23312
	ds_read_b128 v[114:117], v97 offset:23568
	s_waitcnt lgkmcnt(8)
; NI void dn_chunk_local(const P& p, int dh, int n, char* lds) {
;     ...
;       for (int i = hb * 32; i < hb * 32 + 32; ++i) {
;         float a = x[i];
; #pragma unroll
;         for (int j = 0; j < i; ++j) a -= Ls[i * 64 + j] * x[j];
;         x[i] = a;
;         if ((i & 3) == 3) __builtin_amdgcn_sched_barrier(0);
;       }
	v_fma_f32 v31, -v20, v42, v31
	v_fma_f32 v32, -v20, v46, v32
	v_fma_f32 v31, -v21, v43, v31
	v_fma_f32 v32, -v21, v47, v32
	v_fma_f32 v31, -v22, v44, v31
	v_fma_f32 v32, -v22, v48, v32
	v_fma_f32 v31, -v23, v45, v31
	v_fma_f32 v32, -v23, v49, v32
	ds_read_b128 v[42:45], v97 offset:23328
	ds_read_b128 v[46:49], v97 offset:23584
	s_waitcnt lgkmcnt(8)
	v_fma_f32 v31, -v24, v84, v31
	v_fma_f32 v32, -v24, v88, v32
	v_fma_f32 v31, -v25, v85, v31
	v_fma_f32 v32, -v25, v89, v32
	v_fma_f32 v31, -v26, v86, v31
	v_fma_f32 v32, -v26, v90, v32
	v_fma_f32 v31, -v27, v87, v31
	v_fma_f32 v32, -v27, v91, v32
	ds_read_b128 v[84:87], v97 offset:23344
	ds_read_b128 v[88:91], v97 offset:23600
	s_waitcnt lgkmcnt(8)
	v_fma_f32 v31, -v28, v92, v31
	v_fma_f32 v32, -v28, v98, v32
	v_fma_f32 v31, -v29, v93, v31
	v_fma_f32 v32, -v29, v99, v32
	v_fma_f32 v31, -v30, v94, v31
	v_fma_f32 v32, -v30, v100, v32
	v_fma_f32 v32, -v31, v101, v32
	ds_read_b128 v[92:95], v97 offset:23360
	ds_read_b128 v[98:101], v97 offset:23616
	s_waitcnt lgkmcnt(8)
	v_fma_f32 v33, -v8, v102, v33
	v_fma_f32 v34, -v8, v106, v34
	v_fma_f32 v33, -v9, v103, v33
	v_fma_f32 v34, -v9, v107, v34
	v_fma_f32 v33, -v10, v104, v33
	v_fma_f32 v34, -v10, v108, v34
	v_fma_f32 v33, -v11, v105, v33
	v_fma_f32 v34, -v11, v109, v34
	ds_read_b128 v[102:105], v97 offset:23376
	ds_read_b128 v[106:109], v97 offset:23632
	s_waitcnt lgkmcnt(8)
	v_fma_f32 v33, -v12, v110, v33
	v_fma_f32 v34, -v12, v114, v34
	v_fma_f32 v33, -v13, v111, v33
	v_fma_f32 v34, -v13, v115, v34
	v_fma_f32 v33, -v14, v112, v33
	v_fma_f32 v34, -v14, v116, v34
	v_fma_f32 v33, -v15, v113, v33
	v_fma_f32 v34, -v15, v117, v34
	ds_read_b128 v[110:113], v97 offset:23392
	ds_read_b128 v[114:117], v97 offset:23648
	s_waitcnt lgkmcnt(8)
	v_fma_f32 v33, -v16, v42, v33
	v_fma_f32 v34, -v16, v46, v34
	v_fma_f32 v33, -v17, v43, v33
	v_fma_f32 v34, -v17, v47, v34
	v_fma_f32 v33, -v18, v44, v33
	v_fma_f32 v34, -v18, v48, v34
	v_fma_f32 v33, -v19, v45, v33
	v_fma_f32 v34, -v19, v49, v34
	ds_read_b128 v[42:45], v97 offset:23808
	ds_read_b128 v[46:49], v97 offset:24064
	s_waitcnt lgkmcnt(8)
	v_fma_f32 v33, -v20, v84, v33
	v_fma_f32 v34, -v20, v88, v34
	v_fma_f32 v33, -v21, v85, v33
	v_fma_f32 v34, -v21, v89, v34
	v_fma_f32 v33, -v22, v86, v33
	v_fma_f32 v34, -v22, v90, v34
	v_fma_f32 v33, -v23, v87, v33
	v_fma_f32 v34, -v23, v91, v34
	ds_read_b128 v[84:87], v97 offset:23824
	ds_read_b128 v[88:91], v97 offset:24080
	s_waitcnt lgkmcnt(8)
	v_fma_f32 v33, -v24, v92, v33
	v_fma_f32 v34, -v24, v98, v34
	v_fma_f32 v33, -v25, v93, v33
	v_fma_f32 v34, -v25, v99, v34
	v_fma_f32 v33, -v26, v94, v33
	v_fma_f32 v34, -v26, v100, v34
	v_fma_f32 v33, -v27, v95, v33
	v_fma_f32 v34, -v27, v101, v34
	ds_read_b128 v[92:95], v97 offset:23840
	ds_read_b128 v[98:101], v97 offset:24096
	s_waitcnt lgkmcnt(8)
	v_fma_f32 v33, -v28, v102, v33
	v_fma_f32 v34, -v28, v106, v34
	v_fma_f32 v33, -v29, v103, v33
	v_fma_f32 v34, -v29, v107, v34
	v_fma_f32 v33, -v30, v104, v33
	v_fma_f32 v34, -v30, v108, v34
	v_fma_f32 v33, -v31, v105, v33
	v_fma_f32 v34, -v31, v109, v34
	ds_read_b128 v[102:105], v97 offset:23856
	ds_read_b128 v[106:109], v97 offset:24112
	s_waitcnt lgkmcnt(8)
	v_fma_f32 v33, -v32, v110, v33
	v_fma_f32 v34, -v32, v114, v34
	v_fma_f32 v34, -v33, v115, v34
	ds_read_b128 v[110:113], v97 offset:23872
	ds_read_b128 v[114:117], v97 offset:24128
	s_waitcnt lgkmcnt(8)
	v_fma_f32 v35, -v8, v42, v35
	v_fma_f32 v36, -v8, v46, v36
	v_fma_f32 v35, -v9, v43, v35
	v_fma_f32 v36, -v9, v47, v36
	v_fma_f32 v35, -v10, v44, v35
	v_fma_f32 v36, -v10, v48, v36
	v_fma_f32 v35, -v11, v45, v35
	v_fma_f32 v36, -v11, v49, v36
	ds_read_b128 v[42:45], v97 offset:23888
	ds_read_b128 v[46:49], v97 offset:24144
	s_waitcnt lgkmcnt(8)
	v_fma_f32 v35, -v12, v84, v35
	v_fma_f32 v36, -v12, v88, v36
	v_fma_f32 v35, -v13, v85, v35
	v_fma_f32 v36, -v13, v89, v36
	v_fma_f32 v35, -v14, v86, v35
	v_fma_f32 v36, -v14, v90, v36
	v_fma_f32 v35, -v15, v87, v35
	v_fma_f32 v36, -v15, v91, v36
	ds_read_b128 v[84:87], v97 offset:23904
	ds_read_b128 v[88:91], v97 offset:24160
	s_waitcnt lgkmcnt(8)
	v_fma_f32 v35, -v16, v92, v35
	v_fma_f32 v36, -v16, v98, v36
	v_fma_f32 v35, -v17, v93, v35
	v_fma_f32 v36, -v17, v99, v36
	v_fma_f32 v35, -v18, v94, v35
	v_fma_f32 v36, -v18, v100, v36
	v_fma_f32 v35, -v19, v95, v35
	v_fma_f32 v36, -v19, v101, v36
	ds_read_b128 v[92:95], v97 offset:24320
	ds_read_b128 v[98:101], v97 offset:24576
	s_waitcnt lgkmcnt(8)
	v_fma_f32 v35, -v20, v102, v35
	v_fma_f32 v36, -v20, v106, v36
	v_fma_f32 v35, -v21, v103, v35
	v_fma_f32 v36, -v21, v107, v36
	v_fma_f32 v35, -v22, v104, v35
	v_fma_f32 v36, -v22, v108, v36
	v_fma_f32 v35, -v23, v105, v35
	v_fma_f32 v36, -v23, v109, v36
	ds_read_b128 v[102:105], v97 offset:24336
	ds_read_b128 v[106:109], v97 offset:24592
	s_waitcnt lgkmcnt(8)
	v_fma_f32 v35, -v24, v110, v35
	v_fma_f32 v36, -v24, v114, v36
	v_fma_f32 v35, -v25, v111, v35
	v_fma_f32 v36, -v25, v115, v36
	v_fma_f32 v35, -v26, v112, v35
	v_fma_f32 v36, -v26, v116, v36
	v_fma_f32 v35, -v27, v113, v35
	v_fma_f32 v36, -v27, v117, v36
	ds_read_b128 v[110:113], v97 offset:24352
	ds_read_b128 v[114:117], v97 offset:24608
	s_waitcnt lgkmcnt(8)
	v_fma_f32 v35, -v28, v42, v35
	v_fma_f32 v36, -v28, v46, v36
	v_fma_f32 v35, -v29, v43, v35
	v_fma_f32 v36, -v29, v47, v36
	v_fma_f32 v35, -v30, v44, v35
	v_fma_f32 v36, -v30, v48, v36
	v_fma_f32 v35, -v31, v45, v35
	v_fma_f32 v36, -v31, v49, v36
	ds_read_b128 v[42:45], v97 offset:24368
	ds_read_b128 v[46:49], v97 offset:24624
	s_waitcnt lgkmcnt(8)
; NI void dn_chunk_local(const P& p, int dh, int n, char* lds) {
;     ...
;       for (int i = hb * 32; i < hb * 32 + 32; ++i) {
;         float a = x[i];
; #pragma unroll
;         for (int j = 0; j < i; ++j) a -= Ls[i * 64 + j] * x[j];
;         x[i] = a;
;         if ((i & 3) == 3) __builtin_amdgcn_sched_barrier(0);
;       }
	v_fma_f32 v35, -v32, v84, v35
	v_fma_f32 v36, -v32, v88, v36
	v_fma_f32 v35, -v33, v85, v35
	v_fma_f32 v36, -v33, v89, v36
	v_fma_f32 v35, -v34, v86, v35
	v_fma_f32 v36, -v34, v90, v36
	v_fma_f32 v36, -v35, v91, v36
	ds_read_b128 v[84:87], v97 offset:24384
	ds_read_b128 v[88:91], v97 offset:24640
	s_waitcnt lgkmcnt(8)
	v_fma_f32 v37, -v8, v92, v37
	v_fma_f32 v38, -v8, v98, v38
	v_fma_f32 v37, -v9, v93, v37
	v_fma_f32 v38, -v9, v99, v38
	v_fma_f32 v37, -v10, v94, v37
	v_fma_f32 v38, -v10, v100, v38
	v_fma_f32 v37, -v11, v95, v37
	v_fma_f32 v38, -v11, v101, v38
	ds_read_b128 v[92:95], v97 offset:24400
	ds_read_b128 v[98:101], v97 offset:24656
	s_waitcnt lgkmcnt(8)
	v_fma_f32 v37, -v12, v102, v37
	v_fma_f32 v38, -v12, v106, v38
	v_fma_f32 v37, -v13, v103, v37
	v_fma_f32 v38, -v13, v107, v38
	v_fma_f32 v37, -v14, v104, v37
	v_fma_f32 v38, -v14, v108, v38
	v_fma_f32 v37, -v15, v105, v37
	v_fma_f32 v38, -v15, v109, v38
	ds_read_b128 v[102:105], v97 offset:24416
	ds_read_b128 v[106:109], v97 offset:24672
	s_waitcnt lgkmcnt(8)
	v_fma_f32 v37, -v16, v110, v37
	v_fma_f32 v38, -v16, v114, v38
	v_fma_f32 v37, -v17, v111, v37
	v_fma_f32 v38, -v17, v115, v38
	v_fma_f32 v37, -v18, v112, v37
	v_fma_f32 v38, -v18, v116, v38
	v_fma_f32 v37, -v19, v113, v37
	v_fma_f32 v38, -v19, v117, v38
	ds_read_b128 v[110:113], v97 offset:24432
	ds_read_b128 v[114:117], v97 offset:24688
	s_waitcnt lgkmcnt(8)
	v_fma_f32 v37, -v20, v42, v37
	v_fma_f32 v38, -v20, v46, v38
	v_fma_f32 v37, -v21, v43, v37
	v_fma_f32 v38, -v21, v47, v38
	v_fma_f32 v37, -v22, v44, v37
	v_fma_f32 v38, -v22, v48, v38
	v_fma_f32 v37, -v23, v45, v37
	v_fma_f32 v38, -v23, v49, v38
	ds_read_b128 v[42:45], v97 offset:24832
	ds_read_b128 v[46:49], v97 offset:25088
	s_waitcnt lgkmcnt(8)
	v_fma_f32 v37, -v24, v84, v37
	v_fma_f32 v38, -v24, v88, v38
	v_fma_f32 v37, -v25, v85, v37
	v_fma_f32 v38, -v25, v89, v38
	v_fma_f32 v37, -v26, v86, v37
	v_fma_f32 v38, -v26, v90, v38
	v_fma_f32 v37, -v27, v87, v37
	v_fma_f32 v38, -v27, v91, v38
	ds_read_b128 v[84:87], v97 offset:24848
	ds_read_b128 v[88:91], v97 offset:25104
	s_waitcnt lgkmcnt(8)
	v_fma_f32 v37, -v28, v92, v37
	v_fma_f32 v38, -v28, v98, v38
	v_fma_f32 v37, -v29, v93, v37
	v_fma_f32 v38, -v29, v99, v38
	v_fma_f32 v37, -v30, v94, v37
	v_fma_f32 v38, -v30, v100, v38
	v_fma_f32 v37, -v31, v95, v37
	v_fma_f32 v38, -v31, v101, v38
	ds_read_b128 v[92:95], v97 offset:24864
	ds_read_b128 v[98:101], v97 offset:25120
	s_waitcnt lgkmcnt(8)
	v_fma_f32 v37, -v32, v102, v37
	v_fma_f32 v38, -v32, v106, v38
	v_fma_f32 v37, -v33, v103, v37
	v_fma_f32 v38, -v33, v107, v38
	v_fma_f32 v37, -v34, v104, v37
	v_fma_f32 v38, -v34, v108, v38
	v_fma_f32 v37, -v35, v105, v37
	v_fma_f32 v38, -v35, v109, v38
	ds_read_b128 v[102:105], v97 offset:24880
	ds_read_b128 v[106:109], v97 offset:25136
	s_waitcnt lgkmcnt(8)
	v_fma_f32 v37, -v36, v110, v37
	v_fma_f32 v38, -v36, v114, v38
	v_fma_f32 v38, -v37, v115, v38
	ds_read_b128 v[110:113], v97 offset:24896
	ds_read_b128 v[114:117], v97 offset:25152
	s_waitcnt lgkmcnt(8)
	v_fma_f32 v39, -v8, v42, v39
	v_fma_f32 v52, -v8, v46, v52
	v_fma_f32 v39, -v9, v43, v39
	v_fma_f32 v52, -v9, v47, v52
	v_fma_f32 v39, -v10, v44, v39
	v_fma_f32 v52, -v10, v48, v52
	v_fma_f32 v39, -v11, v45, v39
	v_fma_f32 v52, -v11, v49, v52
	ds_read_b128 v[42:45], v97 offset:24912
	ds_read_b128 v[46:49], v97 offset:25168
	s_waitcnt lgkmcnt(8)
	v_fma_f32 v39, -v12, v84, v39
	v_fma_f32 v52, -v12, v88, v52
	v_fma_f32 v39, -v13, v85, v39
	v_fma_f32 v52, -v13, v89, v52
	v_fma_f32 v39, -v14, v86, v39
	v_fma_f32 v52, -v14, v90, v52
	v_fma_f32 v39, -v15, v87, v39
	v_fma_f32 v52, -v15, v91, v52
	ds_read_b128 v[84:87], v97 offset:24928
	ds_read_b128 v[88:91], v97 offset:25184
	s_waitcnt lgkmcnt(8)
	v_fma_f32 v39, -v16, v92, v39
	v_fma_f32 v52, -v16, v98, v52
	v_fma_f32 v39, -v17, v93, v39
	v_fma_f32 v52, -v17, v99, v52
	v_fma_f32 v39, -v18, v94, v39
	v_fma_f32 v52, -v18, v100, v52
	v_fma_f32 v39, -v19, v95, v39
	v_fma_f32 v52, -v19, v101, v52
	ds_read_b128 v[92:95], v97 offset:24944
	ds_read_b128 v[98:101], v97 offset:25200
	s_waitcnt lgkmcnt(8)
	v_fma_f32 v39, -v20, v102, v39
	v_fma_f32 v52, -v20, v106, v52
	v_fma_f32 v39, -v21, v103, v39
	v_fma_f32 v52, -v21, v107, v52
	v_fma_f32 v39, -v22, v104, v39
	v_fma_f32 v52, -v22, v108, v52
	v_fma_f32 v39, -v23, v105, v39
	v_fma_f32 v52, -v23, v109, v52
	ds_read_b128 v[102:105], v97 offset:25344
	ds_read_b128 v[106:109], v97 offset:25600
	s_waitcnt lgkmcnt(8)
	v_fma_f32 v39, -v24, v110, v39
	v_fma_f32 v52, -v24, v114, v52
	v_fma_f32 v39, -v25, v111, v39
	v_fma_f32 v52, -v25, v115, v52
	v_fma_f32 v39, -v26, v112, v39
	v_fma_f32 v52, -v26, v116, v52
	v_fma_f32 v39, -v27, v113, v39
	v_fma_f32 v52, -v27, v117, v52
	ds_read_b128 v[110:113], v97 offset:25360
	ds_read_b128 v[114:117], v97 offset:25616
	s_waitcnt lgkmcnt(8)
	v_fma_f32 v39, -v28, v42, v39
	v_fma_f32 v52, -v28, v46, v52
	v_fma_f32 v39, -v29, v43, v39
	v_fma_f32 v52, -v29, v47, v52
	v_fma_f32 v39, -v30, v44, v39
	v_fma_f32 v52, -v30, v48, v52
	v_fma_f32 v39, -v31, v45, v39
	v_fma_f32 v52, -v31, v49, v52
	ds_read_b128 v[42:45], v97 offset:25376
	ds_read_b128 v[46:49], v97 offset:25632
	s_waitcnt lgkmcnt(8)
	v_fma_f32 v39, -v32, v84, v39
	v_fma_f32 v52, -v32, v88, v52
	v_fma_f32 v39, -v33, v85, v39
	v_fma_f32 v52, -v33, v89, v52
	v_fma_f32 v39, -v34, v86, v39
	v_fma_f32 v52, -v34, v90, v52
	v_fma_f32 v39, -v35, v87, v39
	v_fma_f32 v52, -v35, v91, v52
	ds_read_b128 v[84:87], v97 offset:25392
	ds_read_b128 v[88:91], v97 offset:25648
	s_waitcnt lgkmcnt(8)
; NI void dn_chunk_local(const P& p, int dh, int n, char* lds) {
;     ...
;       for (int i = hb * 32; i < hb * 32 + 32; ++i) {
;         float a = x[i];
; #pragma unroll
;         for (int j = 0; j < i; ++j) a -= Ls[i * 64 + j] * x[j];
;         x[i] = a;
;         if ((i & 3) == 3) __builtin_amdgcn_sched_barrier(0);
;       }
	v_fma_f32 v39, -v36, v92, v39
	v_fma_f32 v52, -v36, v98, v52
	v_fma_f32 v39, -v37, v93, v39
	v_fma_f32 v52, -v37, v99, v52
	v_fma_f32 v39, -v38, v94, v39
	v_fma_f32 v52, -v38, v100, v52
	v_fma_f32 v52, -v39, v101, v52
	ds_read_b128 v[92:95], v97 offset:25408
	ds_read_b128 v[98:101], v97 offset:25664
	s_waitcnt lgkmcnt(8)
	v_fma_f32 v53, -v8, v102, v53
	v_fma_f32 v54, -v8, v106, v54
	v_fma_f32 v53, -v9, v103, v53
	v_fma_f32 v54, -v9, v107, v54
	v_fma_f32 v53, -v10, v104, v53
	v_fma_f32 v54, -v10, v108, v54
	v_fma_f32 v53, -v11, v105, v53
	v_fma_f32 v54, -v11, v109, v54
	ds_read_b128 v[102:105], v97 offset:25424
	ds_read_b128 v[106:109], v97 offset:25680
	s_waitcnt lgkmcnt(8)
	v_fma_f32 v53, -v12, v110, v53
	v_fma_f32 v54, -v12, v114, v54
	v_fma_f32 v53, -v13, v111, v53
	v_fma_f32 v54, -v13, v115, v54
	v_fma_f32 v53, -v14, v112, v53
	v_fma_f32 v54, -v14, v116, v54
	v_fma_f32 v53, -v15, v113, v53
	v_fma_f32 v54, -v15, v117, v54
	ds_read_b128 v[110:113], v97 offset:25440
	ds_read_b128 v[114:117], v97 offset:25696
	s_waitcnt lgkmcnt(8)
	v_fma_f32 v53, -v16, v42, v53
	v_fma_f32 v54, -v16, v46, v54
	v_fma_f32 v53, -v17, v43, v53
	v_fma_f32 v54, -v17, v47, v54
	v_fma_f32 v53, -v18, v44, v53
	v_fma_f32 v54, -v18, v48, v54
	v_fma_f32 v53, -v19, v45, v53
	v_fma_f32 v54, -v19, v49, v54
	ds_read_b128 v[42:45], v97 offset:25456
	ds_read_b128 v[46:49], v97 offset:25712
	s_waitcnt lgkmcnt(8)
	v_fma_f32 v53, -v20, v84, v53
	v_fma_f32 v54, -v20, v88, v54
	v_fma_f32 v53, -v21, v85, v53
	v_fma_f32 v54, -v21, v89, v54
	v_fma_f32 v53, -v22, v86, v53
	v_fma_f32 v54, -v22, v90, v54
	v_fma_f32 v53, -v23, v87, v53
	v_fma_f32 v54, -v23, v91, v54
	ds_read_b128 v[84:87], v97 offset:25472
	ds_read_b128 v[88:91], v97 offset:25728
	s_waitcnt lgkmcnt(8)
	v_fma_f32 v53, -v24, v92, v53
	v_fma_f32 v54, -v24, v98, v54
	v_fma_f32 v53, -v25, v93, v53
	v_fma_f32 v54, -v25, v99, v54
	v_fma_f32 v53, -v26, v94, v53
	v_fma_f32 v54, -v26, v100, v54
	v_fma_f32 v53, -v27, v95, v53
	v_fma_f32 v54, -v27, v101, v54
	ds_read_b128 v[92:95], v97 offset:25856
	ds_read_b128 v[98:101], v97 offset:26112
	s_waitcnt lgkmcnt(8)
	v_fma_f32 v53, -v28, v102, v53
	v_fma_f32 v54, -v28, v106, v54
	v_fma_f32 v53, -v29, v103, v53
	v_fma_f32 v54, -v29, v107, v54
	v_fma_f32 v53, -v30, v104, v53
	v_fma_f32 v54, -v30, v108, v54
	v_fma_f32 v53, -v31, v105, v53
	v_fma_f32 v54, -v31, v109, v54
	ds_read_b128 v[102:105], v97 offset:25872
	ds_read_b128 v[106:109], v97 offset:26128
	s_waitcnt lgkmcnt(8)
	v_fma_f32 v53, -v32, v110, v53
	v_fma_f32 v54, -v32, v114, v54
	v_fma_f32 v53, -v33, v111, v53
	v_fma_f32 v54, -v33, v115, v54
	v_fma_f32 v53, -v34, v112, v53
	v_fma_f32 v54, -v34, v116, v54
	v_fma_f32 v53, -v35, v113, v53
	v_fma_f32 v54, -v35, v117, v54
	ds_read_b128 v[110:113], v97 offset:25888
	ds_read_b128 v[114:117], v97 offset:26144
	s_waitcnt lgkmcnt(8)
	v_fma_f32 v53, -v36, v42, v53
	v_fma_f32 v54, -v36, v46, v54
	v_fma_f32 v53, -v37, v43, v53
	v_fma_f32 v54, -v37, v47, v54
	v_fma_f32 v53, -v38, v44, v53
	v_fma_f32 v54, -v38, v48, v54
	v_fma_f32 v53, -v39, v45, v53
	v_fma_f32 v54, -v39, v49, v54
	ds_read_b128 v[42:45], v97 offset:25904
	ds_read_b128 v[46:49], v97 offset:26160
	s_waitcnt lgkmcnt(8)
	v_fma_f32 v53, -v52, v84, v53
	v_fma_f32 v54, -v52, v88, v54
	v_fma_f32 v54, -v53, v89, v54
	ds_read_b128 v[84:87], v97 offset:25920
	ds_read_b128 v[88:91], v97 offset:26176
	s_waitcnt lgkmcnt(8)
	v_fma_f32 v55, -v8, v92, v55
	v_fma_f32 v56, -v8, v98, v56
	v_fma_f32 v55, -v9, v93, v55
	v_fma_f32 v56, -v9, v99, v56
	v_fma_f32 v55, -v10, v94, v55
	v_fma_f32 v56, -v10, v100, v56
	v_fma_f32 v55, -v11, v95, v55
	v_fma_f32 v56, -v11, v101, v56
	ds_read_b128 v[92:95], v97 offset:25936
	ds_read_b128 v[98:101], v97 offset:26192
	s_waitcnt lgkmcnt(8)
	v_fma_f32 v55, -v12, v102, v55
	v_fma_f32 v56, -v12, v106, v56
	v_fma_f32 v55, -v13, v103, v55
	v_fma_f32 v56, -v13, v107, v56
	v_fma_f32 v55, -v14, v104, v55
	v_fma_f32 v56, -v14, v108, v56
	v_fma_f32 v55, -v15, v105, v55
	v_fma_f32 v56, -v15, v109, v56
	ds_read_b128 v[102:105], v97 offset:25952
	ds_read_b128 v[106:109], v97 offset:26208
	s_waitcnt lgkmcnt(8)
	v_fma_f32 v55, -v16, v110, v55
	v_fma_f32 v56, -v16, v114, v56
	v_fma_f32 v55, -v17, v111, v55
	v_fma_f32 v56, -v17, v115, v56
	v_fma_f32 v55, -v18, v112, v55
	v_fma_f32 v56, -v18, v116, v56
	v_fma_f32 v55, -v19, v113, v55
	v_fma_f32 v56, -v19, v117, v56
	ds_read_b128 v[110:113], v97 offset:25968
	ds_read_b128 v[114:117], v97 offset:26224
	s_waitcnt lgkmcnt(8)
	v_fma_f32 v55, -v20, v42, v55
	v_fma_f32 v56, -v20, v46, v56
	v_fma_f32 v55, -v21, v43, v55
	v_fma_f32 v56, -v21, v47, v56
	v_fma_f32 v55, -v22, v44, v55
	v_fma_f32 v56, -v22, v48, v56
	v_fma_f32 v55, -v23, v45, v55
	v_fma_f32 v56, -v23, v49, v56
	ds_read_b128 v[42:45], v97 offset:25984
	ds_read_b128 v[46:49], v97 offset:26240
	s_waitcnt lgkmcnt(8)
	v_fma_f32 v55, -v24, v84, v55
	v_fma_f32 v56, -v24, v88, v56
	v_fma_f32 v55, -v25, v85, v55
	v_fma_f32 v56, -v25, v89, v56
	v_fma_f32 v55, -v26, v86, v55
	v_fma_f32 v56, -v26, v90, v56
	v_fma_f32 v55, -v27, v87, v55
	v_fma_f32 v56, -v27, v91, v56
	ds_read_b128 v[84:87], v97 offset:26368
	ds_read_b128 v[88:91], v97 offset:26624
	s_waitcnt lgkmcnt(8)
	v_fma_f32 v55, -v28, v92, v55
	v_fma_f32 v56, -v28, v98, v56
	v_fma_f32 v55, -v29, v93, v55
	v_fma_f32 v56, -v29, v99, v56
	v_fma_f32 v55, -v30, v94, v55
	v_fma_f32 v56, -v30, v100, v56
	v_fma_f32 v55, -v31, v95, v55
	v_fma_f32 v56, -v31, v101, v56
	ds_read_b128 v[92:95], v97 offset:26384
	ds_read_b128 v[98:101], v97 offset:26640
	s_waitcnt lgkmcnt(8)
; NI void dn_chunk_local(const P& p, int dh, int n, char* lds) {
;     ...
;       for (int i = hb * 32; i < hb * 32 + 32; ++i) {
;         float a = x[i];
; #pragma unroll
;         for (int j = 0; j < i; ++j) a -= Ls[i * 64 + j] * x[j];
;         x[i] = a;
;         if ((i & 3) == 3) __builtin_amdgcn_sched_barrier(0);
;       }
	v_fma_f32 v55, -v32, v102, v55
	v_fma_f32 v56, -v32, v106, v56
	v_fma_f32 v55, -v33, v103, v55
	v_fma_f32 v56, -v33, v107, v56
	v_fma_f32 v55, -v34, v104, v55
	v_fma_f32 v56, -v34, v108, v56
	v_fma_f32 v55, -v35, v105, v55
	v_fma_f32 v56, -v35, v109, v56
	ds_read_b128 v[102:105], v97 offset:26400
	ds_read_b128 v[106:109], v97 offset:26656
	s_waitcnt lgkmcnt(8)
	v_fma_f32 v55, -v36, v110, v55
	v_fma_f32 v56, -v36, v114, v56
	v_fma_f32 v55, -v37, v111, v55
	v_fma_f32 v56, -v37, v115, v56
	v_fma_f32 v55, -v38, v112, v55
	v_fma_f32 v56, -v38, v116, v56
	v_fma_f32 v55, -v39, v113, v55
	v_fma_f32 v56, -v39, v117, v56
	ds_read_b128 v[110:113], v97 offset:26416
	ds_read_b128 v[114:117], v97 offset:26672
	s_waitcnt lgkmcnt(8)
	v_fma_f32 v55, -v52, v42, v55
	v_fma_f32 v56, -v52, v46, v56
	v_fma_f32 v55, -v53, v43, v55
	v_fma_f32 v56, -v53, v47, v56
	v_fma_f32 v55, -v54, v44, v55
	v_fma_f32 v56, -v54, v48, v56
	v_fma_f32 v56, -v55, v49, v56
	ds_read_b128 v[42:45], v97 offset:26432
	ds_read_b128 v[46:49], v97 offset:26688
	s_waitcnt lgkmcnt(8)
	v_fma_f32 v57, -v8, v84, v57
	v_fma_f32 v58, -v8, v88, v58
	v_fma_f32 v57, -v9, v85, v57
	v_fma_f32 v58, -v9, v89, v58
	v_fma_f32 v57, -v10, v86, v57
	v_fma_f32 v58, -v10, v90, v58
	v_fma_f32 v57, -v11, v87, v57
	v_fma_f32 v58, -v11, v91, v58
	ds_read_b128 v[84:87], v97 offset:26448
	ds_read_b128 v[88:91], v97 offset:26704
	s_waitcnt lgkmcnt(8)
	v_fma_f32 v57, -v12, v92, v57
	v_fma_f32 v58, -v12, v98, v58
	v_fma_f32 v57, -v13, v93, v57
	v_fma_f32 v58, -v13, v99, v58
	v_fma_f32 v57, -v14, v94, v57
	v_fma_f32 v58, -v14, v100, v58
	v_fma_f32 v57, -v15, v95, v57
	v_fma_f32 v58, -v15, v101, v58
	ds_read_b128 v[92:95], v97 offset:26464
	ds_read_b128 v[98:101], v97 offset:26720
	s_waitcnt lgkmcnt(8)
	v_fma_f32 v57, -v16, v102, v57
	v_fma_f32 v58, -v16, v106, v58
	v_fma_f32 v57, -v17, v103, v57
	v_fma_f32 v58, -v17, v107, v58
	v_fma_f32 v57, -v18, v104, v57
	v_fma_f32 v58, -v18, v108, v58
	v_fma_f32 v57, -v19, v105, v57
	v_fma_f32 v58, -v19, v109, v58
	ds_read_b128 v[102:105], v97 offset:26480
	ds_read_b128 v[106:109], v97 offset:26736
	s_waitcnt lgkmcnt(8)
	v_fma_f32 v57, -v20, v110, v57
	v_fma_f32 v58, -v20, v114, v58
	v_fma_f32 v57, -v21, v111, v57
	v_fma_f32 v58, -v21, v115, v58
	v_fma_f32 v57, -v22, v112, v57
	v_fma_f32 v58, -v22, v116, v58
	v_fma_f32 v57, -v23, v113, v57
	v_fma_f32 v58, -v23, v117, v58
	ds_read_b128 v[110:113], v97 offset:26496
	ds_read_b128 v[114:117], v97 offset:26752
	s_waitcnt lgkmcnt(8)
	v_fma_f32 v57, -v24, v42, v57
	v_fma_f32 v58, -v24, v46, v58
	v_fma_f32 v57, -v25, v43, v57
	v_fma_f32 v58, -v25, v47, v58
	v_fma_f32 v57, -v26, v44, v57
	v_fma_f32 v58, -v26, v48, v58
	v_fma_f32 v57, -v27, v45, v57
	v_fma_f32 v58, -v27, v49, v58
	ds_read_b128 v[42:45], v97 offset:26512
	ds_read_b128 v[46:49], v97 offset:26768
	s_waitcnt lgkmcnt(8)
	v_fma_f32 v57, -v28, v84, v57
	v_fma_f32 v58, -v28, v88, v58
	v_fma_f32 v57, -v29, v85, v57
	v_fma_f32 v58, -v29, v89, v58
	v_fma_f32 v57, -v30, v86, v57
	v_fma_f32 v58, -v30, v90, v58
	v_fma_f32 v57, -v31, v87, v57
	v_fma_f32 v58, -v31, v91, v58
	ds_read_b128 v[84:87], v97 offset:26880
	ds_read_b128 v[88:91], v97 offset:27136
	s_waitcnt lgkmcnt(8)
	v_fma_f32 v57, -v32, v92, v57
	v_fma_f32 v58, -v32, v98, v58
	v_fma_f32 v57, -v33, v93, v57
	v_fma_f32 v58, -v33, v99, v58
	v_fma_f32 v57, -v34, v94, v57
	v_fma_f32 v58, -v34, v100, v58
	v_fma_f32 v57, -v35, v95, v57
	v_fma_f32 v58, -v35, v101, v58
	ds_read_b128 v[92:95], v97 offset:26896
	ds_read_b128 v[98:101], v97 offset:27152
	s_waitcnt lgkmcnt(8)
	v_fma_f32 v57, -v36, v102, v57
	v_fma_f32 v58, -v36, v106, v58
	v_fma_f32 v57, -v37, v103, v57
	v_fma_f32 v58, -v37, v107, v58
	v_fma_f32 v57, -v38, v104, v57
	v_fma_f32 v58, -v38, v108, v58
	v_fma_f32 v57, -v39, v105, v57
	v_fma_f32 v58, -v39, v109, v58
	ds_read_b128 v[102:105], v97 offset:26912
	ds_read_b128 v[106:109], v97 offset:27168
	s_waitcnt lgkmcnt(8)
	v_fma_f32 v57, -v52, v110, v57
	v_fma_f32 v58, -v52, v114, v58
	v_fma_f32 v57, -v53, v111, v57
	v_fma_f32 v58, -v53, v115, v58
	v_fma_f32 v57, -v54, v112, v57
	v_fma_f32 v58, -v54, v116, v58
	v_fma_f32 v57, -v55, v113, v57
	v_fma_f32 v58, -v55, v117, v58
	ds_read_b128 v[110:113], v97 offset:26928
	ds_read_b128 v[114:117], v97 offset:27184
	s_waitcnt lgkmcnt(8)
	v_fma_f32 v57, -v56, v42, v57
	v_fma_f32 v58, -v56, v46, v58
	v_fma_f32 v58, -v57, v47, v58
	ds_read_b128 v[42:45], v97 offset:26944
	ds_read_b128 v[46:49], v97 offset:27200
	s_waitcnt lgkmcnt(8)
	v_fma_f32 v59, -v8, v84, v59
	v_fma_f32 v60, -v8, v88, v60
	v_fma_f32 v59, -v9, v85, v59
	v_fma_f32 v60, -v9, v89, v60
	v_fma_f32 v59, -v10, v86, v59
	v_fma_f32 v60, -v10, v90, v60
	v_fma_f32 v59, -v11, v87, v59
	v_fma_f32 v60, -v11, v91, v60
	ds_read_b128 v[84:87], v97 offset:26960
	ds_read_b128 v[88:91], v97 offset:27216
	s_waitcnt lgkmcnt(8)
	v_fma_f32 v59, -v12, v92, v59
	v_fma_f32 v60, -v12, v98, v60
	v_fma_f32 v59, -v13, v93, v59
	v_fma_f32 v60, -v13, v99, v60
	v_fma_f32 v59, -v14, v94, v59
	v_fma_f32 v60, -v14, v100, v60
	v_fma_f32 v59, -v15, v95, v59
	v_fma_f32 v60, -v15, v101, v60
	ds_read_b128 v[92:95], v97 offset:26976
	ds_read_b128 v[98:101], v97 offset:27232
	s_waitcnt lgkmcnt(8)
	v_fma_f32 v59, -v16, v102, v59
	v_fma_f32 v60, -v16, v106, v60
	v_fma_f32 v59, -v17, v103, v59
	v_fma_f32 v60, -v17, v107, v60
	v_fma_f32 v59, -v18, v104, v59
	v_fma_f32 v60, -v18, v108, v60
	v_fma_f32 v59, -v19, v105, v59
	v_fma_f32 v60, -v19, v109, v60
	ds_read_b128 v[102:105], v97 offset:26992
	ds_read_b128 v[106:109], v97 offset:27248
	s_waitcnt lgkmcnt(8)
; NI void dn_chunk_local(const P& p, int dh, int n, char* lds) {
;     ...
;       for (int i = hb * 32; i < hb * 32 + 32; ++i) {
;         float a = x[i];
; #pragma unroll
;         for (int j = 0; j < i; ++j) a -= Ls[i * 64 + j] * x[j];
;         x[i] = a;
;         if ((i & 3) == 3) __builtin_amdgcn_sched_barrier(0);
;       }
	v_fma_f32 v59, -v20, v110, v59
	v_fma_f32 v60, -v20, v114, v60
	v_fma_f32 v59, -v21, v111, v59
	v_fma_f32 v60, -v21, v115, v60
	v_fma_f32 v59, -v22, v112, v59
	v_fma_f32 v60, -v22, v116, v60
	v_fma_f32 v59, -v23, v113, v59
	v_fma_f32 v60, -v23, v117, v60
	ds_read_b128 v[110:113], v97 offset:27008
	ds_read_b128 v[114:117], v97 offset:27264
	s_waitcnt lgkmcnt(8)
	v_fma_f32 v59, -v24, v42, v59
	v_fma_f32 v60, -v24, v46, v60
	v_fma_f32 v59, -v25, v43, v59
	v_fma_f32 v60, -v25, v47, v60
	v_fma_f32 v59, -v26, v44, v59
	v_fma_f32 v60, -v26, v48, v60
	v_fma_f32 v59, -v27, v45, v59
	v_fma_f32 v60, -v27, v49, v60
	ds_read_b128 v[42:45], v97 offset:27024
	ds_read_b128 v[46:49], v97 offset:27280
	s_waitcnt lgkmcnt(8)
	v_fma_f32 v59, -v28, v84, v59
	v_fma_f32 v60, -v28, v88, v60
	v_fma_f32 v59, -v29, v85, v59
	v_fma_f32 v60, -v29, v89, v60
	v_fma_f32 v59, -v30, v86, v59
	v_fma_f32 v60, -v30, v90, v60
	v_fma_f32 v59, -v31, v87, v59
	v_fma_f32 v60, -v31, v91, v60
	ds_read_b128 v[84:87], v97 offset:27392
	ds_read_b128 v[88:91], v97 offset:27648
	s_waitcnt lgkmcnt(8)
	v_fma_f32 v59, -v32, v92, v59
	v_fma_f32 v60, -v32, v98, v60
	v_fma_f32 v59, -v33, v93, v59
	v_fma_f32 v60, -v33, v99, v60
	v_fma_f32 v59, -v34, v94, v59
	v_fma_f32 v60, -v34, v100, v60
	v_fma_f32 v59, -v35, v95, v59
	v_fma_f32 v60, -v35, v101, v60
	ds_read_b128 v[92:95], v97 offset:27408
	ds_read_b128 v[98:101], v97 offset:27664
	s_waitcnt lgkmcnt(8)
	v_fma_f32 v59, -v36, v102, v59
	v_fma_f32 v60, -v36, v106, v60
	v_fma_f32 v59, -v37, v103, v59
	v_fma_f32 v60, -v37, v107, v60
	v_fma_f32 v59, -v38, v104, v59
	v_fma_f32 v60, -v38, v108, v60
	v_fma_f32 v59, -v39, v105, v59
	v_fma_f32 v60, -v39, v109, v60
	ds_read_b128 v[102:105], v97 offset:27424
	ds_read_b128 v[106:109], v97 offset:27680
	s_waitcnt lgkmcnt(8)
	v_fma_f32 v59, -v52, v110, v59
	v_fma_f32 v60, -v52, v114, v60
	v_fma_f32 v59, -v53, v111, v59
	v_fma_f32 v60, -v53, v115, v60
	v_fma_f32 v59, -v54, v112, v59
	v_fma_f32 v60, -v54, v116, v60
	v_fma_f32 v59, -v55, v113, v59
	v_fma_f32 v60, -v55, v117, v60
	ds_read_b128 v[110:113], v97 offset:27440
	ds_read_b128 v[114:117], v97 offset:27696
	s_waitcnt lgkmcnt(8)
	v_fma_f32 v59, -v56, v42, v59
	v_fma_f32 v60, -v56, v46, v60
	v_fma_f32 v59, -v57, v43, v59
	v_fma_f32 v60, -v57, v47, v60
	v_fma_f32 v59, -v58, v44, v59
	v_fma_f32 v60, -v58, v48, v60
	v_fma_f32 v60, -v59, v49, v60
	ds_read_b128 v[42:45], v97 offset:27456
	ds_read_b128 v[46:49], v97 offset:27712
	s_waitcnt lgkmcnt(8)
	v_fma_f32 v61, -v8, v84, v61
	v_fma_f32 v62, -v8, v88, v62
	v_fma_f32 v61, -v9, v85, v61
	v_fma_f32 v62, -v9, v89, v62
	v_fma_f32 v61, -v10, v86, v61
	v_fma_f32 v62, -v10, v90, v62
	v_fma_f32 v61, -v11, v87, v61
	v_fma_f32 v62, -v11, v91, v62
	ds_read_b128 v[84:87], v97 offset:27472
	ds_read_b128 v[88:91], v97 offset:27728
	s_waitcnt lgkmcnt(8)
	v_fma_f32 v61, -v12, v92, v61
	v_fma_f32 v62, -v12, v98, v62
	v_fma_f32 v61, -v13, v93, v61
	v_fma_f32 v62, -v13, v99, v62
	v_fma_f32 v61, -v14, v94, v61
	v_fma_f32 v62, -v14, v100, v62
	v_fma_f32 v61, -v15, v95, v61
	v_fma_f32 v62, -v15, v101, v62
	ds_read_b128 v[92:95], v97 offset:27488
	ds_read_b128 v[98:101], v97 offset:27744
	s_waitcnt lgkmcnt(8)
	v_fma_f32 v61, -v16, v102, v61
	v_fma_f32 v62, -v16, v106, v62
	v_fma_f32 v61, -v17, v103, v61
	v_fma_f32 v62, -v17, v107, v62
	v_fma_f32 v61, -v18, v104, v61
	v_fma_f32 v62, -v18, v108, v62
	v_fma_f32 v61, -v19, v105, v61
	v_fma_f32 v62, -v19, v109, v62
	ds_read_b128 v[102:105], v97 offset:27504
	ds_read_b128 v[106:109], v97 offset:27760
	s_waitcnt lgkmcnt(8)
	v_fma_f32 v61, -v20, v110, v61
	v_fma_f32 v62, -v20, v114, v62
	v_fma_f32 v61, -v21, v111, v61
	v_fma_f32 v62, -v21, v115, v62
	v_fma_f32 v61, -v22, v112, v61
	v_fma_f32 v62, -v22, v116, v62
	v_fma_f32 v61, -v23, v113, v61
	v_fma_f32 v62, -v23, v117, v62
	ds_read_b128 v[110:113], v97 offset:27520
	ds_read_b128 v[114:117], v97 offset:27776
	s_waitcnt lgkmcnt(8)
	v_fma_f32 v61, -v24, v42, v61
	v_fma_f32 v62, -v24, v46, v62
	v_fma_f32 v61, -v25, v43, v61
	v_fma_f32 v62, -v25, v47, v62
	v_fma_f32 v61, -v26, v44, v61
	v_fma_f32 v62, -v26, v48, v62
	v_fma_f32 v61, -v27, v45, v61
	v_fma_f32 v62, -v27, v49, v62
	ds_read_b128 v[42:45], v97 offset:27536
	ds_read_b128 v[46:49], v97 offset:27792
	s_waitcnt lgkmcnt(8)
	v_fma_f32 v61, -v28, v84, v61
	v_fma_f32 v62, -v28, v88, v62
	v_fma_f32 v61, -v29, v85, v61
	v_fma_f32 v62, -v29, v89, v62
	v_fma_f32 v61, -v30, v86, v61
	v_fma_f32 v62, -v30, v90, v62
	v_fma_f32 v61, -v31, v87, v61
	v_fma_f32 v62, -v31, v91, v62
	ds_read_b128 v[84:87], v97 offset:27552
	ds_read_b128 v[88:91], v97 offset:27808
	s_waitcnt lgkmcnt(8)
	v_fma_f32 v61, -v32, v92, v61
	v_fma_f32 v62, -v32, v98, v62
	v_fma_f32 v61, -v33, v93, v61
	v_fma_f32 v62, -v33, v99, v62
	v_fma_f32 v61, -v34, v94, v61
	v_fma_f32 v62, -v34, v100, v62
	v_fma_f32 v61, -v35, v95, v61
	v_fma_f32 v62, -v35, v101, v62
	ds_read_b128 v[92:95], v97 offset:27904
	ds_read_b128 v[98:101], v97 offset:28160
	s_waitcnt lgkmcnt(8)
	v_fma_f32 v61, -v36, v102, v61
	v_fma_f32 v62, -v36, v106, v62
	v_fma_f32 v61, -v37, v103, v61
	v_fma_f32 v62, -v37, v107, v62
	v_fma_f32 v61, -v38, v104, v61
	v_fma_f32 v62, -v38, v108, v62
	v_fma_f32 v61, -v39, v105, v61
	v_fma_f32 v62, -v39, v109, v62
	ds_read_b128 v[102:105], v97 offset:27920
	ds_read_b128 v[106:109], v97 offset:28176
	s_waitcnt lgkmcnt(8)
	v_fma_f32 v61, -v52, v110, v61
	v_fma_f32 v62, -v52, v114, v62
	v_fma_f32 v61, -v53, v111, v61
	v_fma_f32 v62, -v53, v115, v62
	v_fma_f32 v61, -v54, v112, v61
	v_fma_f32 v62, -v54, v116, v62
	v_fma_f32 v61, -v55, v113, v61
	v_fma_f32 v62, -v55, v117, v62
	ds_read_b128 v[110:113], v97 offset:27936
	ds_read_b128 v[114:117], v97 offset:28192
	s_waitcnt lgkmcnt(8)
; NI void dn_chunk_local(const P& p, int dh, int n, char* lds) {
;     ...
;       for (int i = hb * 32; i < hb * 32 + 32; ++i) {
;         float a = x[i];
; #pragma unroll
;         for (int j = 0; j < i; ++j) a -= Ls[i * 64 + j] * x[j];
;         x[i] = a;
;         if ((i & 3) == 3) __builtin_amdgcn_sched_barrier(0);
;       }
	v_fma_f32 v61, -v56, v42, v61
	v_fma_f32 v62, -v56, v46, v62
	v_fma_f32 v61, -v57, v43, v61
	v_fma_f32 v62, -v57, v47, v62
	v_fma_f32 v61, -v58, v44, v61
	v_fma_f32 v62, -v58, v48, v62
	v_fma_f32 v61, -v59, v45, v61
	v_fma_f32 v62, -v59, v49, v62
	ds_read_b128 v[42:45], v97 offset:27952
	ds_read_b128 v[46:49], v97 offset:28208
	s_waitcnt lgkmcnt(8)
	v_fma_f32 v61, -v60, v84, v61
	v_fma_f32 v62, -v60, v88, v62
	v_fma_f32 v62, -v61, v89, v62
	ds_read_b128 v[84:87], v97 offset:27968
	ds_read_b128 v[88:91], v97 offset:28224
	s_waitcnt lgkmcnt(8)
	v_fma_f32 v63, -v8, v92, v63
	v_fma_f32 v64, -v8, v98, v64
	v_fma_f32 v63, -v9, v93, v63
	v_fma_f32 v64, -v9, v99, v64
	v_fma_f32 v63, -v10, v94, v63
	v_fma_f32 v64, -v10, v100, v64
	v_fma_f32 v63, -v11, v95, v63
	v_fma_f32 v64, -v11, v101, v64
	ds_read_b128 v[92:95], v97 offset:27984
	ds_read_b128 v[98:101], v97 offset:28240
	s_waitcnt lgkmcnt(8)
	v_fma_f32 v63, -v12, v102, v63
	v_fma_f32 v64, -v12, v106, v64
	v_fma_f32 v63, -v13, v103, v63
	v_fma_f32 v64, -v13, v107, v64
	v_fma_f32 v63, -v14, v104, v63
	v_fma_f32 v64, -v14, v108, v64
	v_fma_f32 v63, -v15, v105, v63
	v_fma_f32 v64, -v15, v109, v64
	ds_read_b128 v[102:105], v97 offset:28000
	ds_read_b128 v[106:109], v97 offset:28256
	s_waitcnt lgkmcnt(8)
	v_fma_f32 v63, -v16, v110, v63
	v_fma_f32 v64, -v16, v114, v64
	v_fma_f32 v63, -v17, v111, v63
	v_fma_f32 v64, -v17, v115, v64
	v_fma_f32 v63, -v18, v112, v63
	v_fma_f32 v64, -v18, v116, v64
	v_fma_f32 v63, -v19, v113, v63
	v_fma_f32 v64, -v19, v117, v64
	ds_read_b128 v[110:113], v97 offset:28016
	ds_read_b128 v[114:117], v97 offset:28272
	s_waitcnt lgkmcnt(8)
	v_fma_f32 v63, -v20, v42, v63
	v_fma_f32 v64, -v20, v46, v64
	v_fma_f32 v63, -v21, v43, v63
	v_fma_f32 v64, -v21, v47, v64
	v_fma_f32 v63, -v22, v44, v63
	v_fma_f32 v64, -v22, v48, v64
	v_fma_f32 v63, -v23, v45, v63
	v_fma_f32 v64, -v23, v49, v64
	ds_read_b128 v[42:45], v97 offset:28032
	ds_read_b128 v[46:49], v97 offset:28288
	s_waitcnt lgkmcnt(8)
	v_fma_f32 v63, -v24, v84, v63
	v_fma_f32 v64, -v24, v88, v64
	v_fma_f32 v63, -v25, v85, v63
	v_fma_f32 v64, -v25, v89, v64
	v_fma_f32 v63, -v26, v86, v63
	v_fma_f32 v64, -v26, v90, v64
	v_fma_f32 v63, -v27, v87, v63
	v_fma_f32 v64, -v27, v91, v64
	ds_read_b128 v[84:87], v97 offset:28048
	ds_read_b128 v[88:91], v97 offset:28304
	s_waitcnt lgkmcnt(8)
	v_fma_f32 v63, -v28, v92, v63
	v_fma_f32 v64, -v28, v98, v64
	v_fma_f32 v63, -v29, v93, v63
	v_fma_f32 v64, -v29, v99, v64
	v_fma_f32 v63, -v30, v94, v63
	v_fma_f32 v64, -v30, v100, v64
	v_fma_f32 v63, -v31, v95, v63
	v_fma_f32 v64, -v31, v101, v64
	ds_read_b128 v[92:95], v97 offset:28064
	ds_read_b128 v[98:101], v97 offset:28320
	s_waitcnt lgkmcnt(8)
	v_fma_f32 v63, -v32, v102, v63
	v_fma_f32 v64, -v32, v106, v64
	v_fma_f32 v63, -v33, v103, v63
	v_fma_f32 v64, -v33, v107, v64
	v_fma_f32 v63, -v34, v104, v63
	v_fma_f32 v64, -v34, v108, v64
	v_fma_f32 v63, -v35, v105, v63
	v_fma_f32 v64, -v35, v109, v64
	ds_read_b128 v[102:105], v97 offset:28416
	ds_read_b128 v[106:109], v97 offset:28672
	s_waitcnt lgkmcnt(8)
	v_fma_f32 v63, -v36, v110, v63
	v_fma_f32 v64, -v36, v114, v64
	v_fma_f32 v63, -v37, v111, v63
	v_fma_f32 v64, -v37, v115, v64
	v_fma_f32 v63, -v38, v112, v63
	v_fma_f32 v64, -v38, v116, v64
	v_fma_f32 v63, -v39, v113, v63
	v_fma_f32 v64, -v39, v117, v64
	ds_read_b128 v[110:113], v97 offset:28432
	ds_read_b128 v[114:117], v97 offset:28688
	s_waitcnt lgkmcnt(8)
	v_fma_f32 v63, -v52, v42, v63
	v_fma_f32 v64, -v52, v46, v64
	v_fma_f32 v63, -v53, v43, v63
	v_fma_f32 v64, -v53, v47, v64
	v_fma_f32 v63, -v54, v44, v63
	v_fma_f32 v64, -v54, v48, v64
	v_fma_f32 v63, -v55, v45, v63
	v_fma_f32 v64, -v55, v49, v64
	ds_read_b128 v[42:45], v97 offset:28448
	ds_read_b128 v[46:49], v97 offset:28704
	s_waitcnt lgkmcnt(8)
	v_fma_f32 v63, -v56, v84, v63
	v_fma_f32 v64, -v56, v88, v64
	v_fma_f32 v63, -v57, v85, v63
	v_fma_f32 v64, -v57, v89, v64
	v_fma_f32 v63, -v58, v86, v63
	v_fma_f32 v64, -v58, v90, v64
	v_fma_f32 v63, -v59, v87, v63
	v_fma_f32 v64, -v59, v91, v64
	ds_read_b128 v[84:87], v97 offset:28464
	ds_read_b128 v[88:91], v97 offset:28720
	s_waitcnt lgkmcnt(8)
	v_fma_f32 v63, -v60, v92, v63
	v_fma_f32 v64, -v60, v98, v64
	v_fma_f32 v63, -v61, v93, v63
	v_fma_f32 v64, -v61, v99, v64
	v_fma_f32 v63, -v62, v94, v63
	v_fma_f32 v64, -v62, v100, v64
	v_fma_f32 v64, -v63, v101, v64
	ds_read_b128 v[92:95], v97 offset:28480
	ds_read_b128 v[98:101], v97 offset:28736
	s_waitcnt lgkmcnt(8)
	v_fma_f32 v65, -v8, v102, v65
	v_fma_f32 v66, -v8, v106, v66
	v_fma_f32 v65, -v9, v103, v65
	v_fma_f32 v66, -v9, v107, v66
	v_fma_f32 v65, -v10, v104, v65
	v_fma_f32 v66, -v10, v108, v66
	v_fma_f32 v65, -v11, v105, v65
	v_fma_f32 v66, -v11, v109, v66
	ds_read_b128 v[102:105], v97 offset:28496
	ds_read_b128 v[106:109], v97 offset:28752
	s_waitcnt lgkmcnt(8)
	v_fma_f32 v65, -v12, v110, v65
	v_fma_f32 v66, -v12, v114, v66
	v_fma_f32 v65, -v13, v111, v65
	v_fma_f32 v66, -v13, v115, v66
	v_fma_f32 v65, -v14, v112, v65
	v_fma_f32 v66, -v14, v116, v66
	v_fma_f32 v65, -v15, v113, v65
	v_fma_f32 v66, -v15, v117, v66
	ds_read_b128 v[110:113], v97 offset:28512
	ds_read_b128 v[114:117], v97 offset:28768
	s_waitcnt lgkmcnt(8)
	v_fma_f32 v65, -v16, v42, v65
	v_fma_f32 v66, -v16, v46, v66
	v_fma_f32 v65, -v17, v43, v65
	v_fma_f32 v66, -v17, v47, v66
	v_fma_f32 v65, -v18, v44, v65
	v_fma_f32 v66, -v18, v48, v66
	v_fma_f32 v65, -v19, v45, v65
	v_fma_f32 v66, -v19, v49, v66
	ds_read_b128 v[42:45], v97 offset:28528
	ds_read_b128 v[46:49], v97 offset:28784
	s_waitcnt lgkmcnt(8)
; NI void dn_chunk_local(const P& p, int dh, int n, char* lds) {
;     ...
;       for (int i = hb * 32; i < hb * 32 + 32; ++i) {
;         float a = x[i];
; #pragma unroll
;         for (int j = 0; j < i; ++j) a -= Ls[i * 64 + j] * x[j];
;         x[i] = a;
;         if ((i & 3) == 3) __builtin_amdgcn_sched_barrier(0);
;       }
	v_fma_f32 v65, -v20, v84, v65
	v_fma_f32 v66, -v20, v88, v66
	v_fma_f32 v65, -v21, v85, v65
	v_fma_f32 v66, -v21, v89, v66
	v_fma_f32 v65, -v22, v86, v65
	v_fma_f32 v66, -v22, v90, v66
	v_fma_f32 v65, -v23, v87, v65
	v_fma_f32 v66, -v23, v91, v66
	ds_read_b128 v[84:87], v97 offset:28544
	ds_read_b128 v[88:91], v97 offset:28800
	s_waitcnt lgkmcnt(8)
	v_fma_f32 v65, -v24, v92, v65
	v_fma_f32 v66, -v24, v98, v66
	v_fma_f32 v65, -v25, v93, v65
	v_fma_f32 v66, -v25, v99, v66
	v_fma_f32 v65, -v26, v94, v65
	v_fma_f32 v66, -v26, v100, v66
	v_fma_f32 v65, -v27, v95, v65
	v_fma_f32 v66, -v27, v101, v66
	ds_read_b128 v[92:95], v97 offset:28560
	ds_read_b128 v[98:101], v97 offset:28816
	s_waitcnt lgkmcnt(8)
	v_fma_f32 v65, -v28, v102, v65
	v_fma_f32 v66, -v28, v106, v66
	v_fma_f32 v65, -v29, v103, v65
	v_fma_f32 v66, -v29, v107, v66
	v_fma_f32 v65, -v30, v104, v65
	v_fma_f32 v66, -v30, v108, v66
	v_fma_f32 v65, -v31, v105, v65
	v_fma_f32 v66, -v31, v109, v66
	ds_read_b128 v[102:105], v97 offset:28576
	ds_read_b128 v[106:109], v97 offset:28832
	s_waitcnt lgkmcnt(8)
	v_fma_f32 v65, -v32, v110, v65
	v_fma_f32 v66, -v32, v114, v66
	v_fma_f32 v65, -v33, v111, v65
	v_fma_f32 v66, -v33, v115, v66
	v_fma_f32 v65, -v34, v112, v65
	v_fma_f32 v66, -v34, v116, v66
	v_fma_f32 v65, -v35, v113, v65
	v_fma_f32 v66, -v35, v117, v66
	ds_read_b128 v[110:113], v97 offset:28592
	ds_read_b128 v[114:117], v97 offset:28848
	s_waitcnt lgkmcnt(8)
	v_fma_f32 v65, -v36, v42, v65
	v_fma_f32 v66, -v36, v46, v66
	v_fma_f32 v65, -v37, v43, v65
	v_fma_f32 v66, -v37, v47, v66
	v_fma_f32 v65, -v38, v44, v65
	v_fma_f32 v66, -v38, v48, v66
	v_fma_f32 v65, -v39, v45, v65
	v_fma_f32 v66, -v39, v49, v66
	ds_read_b128 v[42:45], v97 offset:28928
	ds_read_b128 v[46:49], v97 offset:29184
	s_waitcnt lgkmcnt(8)
	v_fma_f32 v65, -v52, v84, v65
	v_fma_f32 v66, -v52, v88, v66
	v_fma_f32 v65, -v53, v85, v65
	v_fma_f32 v66, -v53, v89, v66
	v_fma_f32 v65, -v54, v86, v65
	v_fma_f32 v66, -v54, v90, v66
	v_fma_f32 v65, -v55, v87, v65
	v_fma_f32 v66, -v55, v91, v66
	ds_read_b128 v[84:87], v97 offset:28944
	ds_read_b128 v[88:91], v97 offset:29200
	s_waitcnt lgkmcnt(8)
	v_fma_f32 v65, -v56, v92, v65
	v_fma_f32 v66, -v56, v98, v66
	v_fma_f32 v65, -v57, v93, v65
	v_fma_f32 v66, -v57, v99, v66
	v_fma_f32 v65, -v58, v94, v65
	v_fma_f32 v66, -v58, v100, v66
	v_fma_f32 v65, -v59, v95, v65
	v_fma_f32 v66, -v59, v101, v66
	ds_read_b128 v[92:95], v97 offset:28960
	ds_read_b128 v[98:101], v97 offset:29216
	s_waitcnt lgkmcnt(8)
	v_fma_f32 v65, -v60, v102, v65
	v_fma_f32 v66, -v60, v106, v66
	v_fma_f32 v65, -v61, v103, v65
	v_fma_f32 v66, -v61, v107, v66
	v_fma_f32 v65, -v62, v104, v65
	v_fma_f32 v66, -v62, v108, v66
	v_fma_f32 v65, -v63, v105, v65
	v_fma_f32 v66, -v63, v109, v66
	ds_read_b128 v[102:105], v97 offset:28976
	ds_read_b128 v[106:109], v97 offset:29232
	s_waitcnt lgkmcnt(8)
	v_fma_f32 v65, -v64, v110, v65
	v_fma_f32 v66, -v64, v114, v66
	v_fma_f32 v66, -v65, v115, v66
	ds_read_b128 v[110:113], v97 offset:28992
	ds_read_b128 v[114:117], v97 offset:29248
	s_waitcnt lgkmcnt(8)
	v_fma_f32 v67, -v8, v42, v67
	v_fma_f32 v68, -v8, v46, v68
	v_fma_f32 v67, -v9, v43, v67
	v_fma_f32 v68, -v9, v47, v68
	v_fma_f32 v67, -v10, v44, v67
	v_fma_f32 v68, -v10, v48, v68
	v_fma_f32 v67, -v11, v45, v67
	v_fma_f32 v68, -v11, v49, v68
	ds_read_b128 v[42:45], v97 offset:29008
	ds_read_b128 v[46:49], v97 offset:29264
	s_waitcnt lgkmcnt(8)
	v_fma_f32 v67, -v12, v84, v67
	v_fma_f32 v68, -v12, v88, v68
	v_fma_f32 v67, -v13, v85, v67
	v_fma_f32 v68, -v13, v89, v68
	v_fma_f32 v67, -v14, v86, v67
	v_fma_f32 v68, -v14, v90, v68
	v_fma_f32 v67, -v15, v87, v67
	v_fma_f32 v68, -v15, v91, v68
	ds_read_b128 v[84:87], v97 offset:29024
	ds_read_b128 v[88:91], v97 offset:29280
	s_waitcnt lgkmcnt(8)
	v_fma_f32 v67, -v16, v92, v67
	v_fma_f32 v68, -v16, v98, v68
	v_fma_f32 v67, -v17, v93, v67
	v_fma_f32 v68, -v17, v99, v68
	v_fma_f32 v67, -v18, v94, v67
	v_fma_f32 v68, -v18, v100, v68
	v_fma_f32 v67, -v19, v95, v67
	v_fma_f32 v68, -v19, v101, v68
	ds_read_b128 v[92:95], v97 offset:29040
	ds_read_b128 v[98:101], v97 offset:29296
	s_waitcnt lgkmcnt(8)
	v_fma_f32 v67, -v20, v102, v67
	v_fma_f32 v68, -v20, v106, v68
	v_fma_f32 v67, -v21, v103, v67
	v_fma_f32 v68, -v21, v107, v68
	v_fma_f32 v67, -v22, v104, v67
	v_fma_f32 v68, -v22, v108, v68
	v_fma_f32 v67, -v23, v105, v67
	v_fma_f32 v68, -v23, v109, v68
	ds_read_b128 v[102:105], v97 offset:29056
	ds_read_b128 v[106:109], v97 offset:29312
	s_waitcnt lgkmcnt(8)
	v_fma_f32 v67, -v24, v110, v67
	v_fma_f32 v68, -v24, v114, v68
	v_fma_f32 v67, -v25, v111, v67
	v_fma_f32 v68, -v25, v115, v68
	v_fma_f32 v67, -v26, v112, v67
	v_fma_f32 v68, -v26, v116, v68
	v_fma_f32 v67, -v27, v113, v67
	v_fma_f32 v68, -v27, v117, v68
	ds_read_b128 v[110:113], v97 offset:29072
	ds_read_b128 v[114:117], v97 offset:29328
	s_waitcnt lgkmcnt(8)
	v_fma_f32 v67, -v28, v42, v67
	v_fma_f32 v68, -v28, v46, v68
	v_fma_f32 v67, -v29, v43, v67
	v_fma_f32 v68, -v29, v47, v68
	v_fma_f32 v67, -v30, v44, v67
	v_fma_f32 v68, -v30, v48, v68
	v_fma_f32 v67, -v31, v45, v67
	v_fma_f32 v68, -v31, v49, v68
	ds_read_b128 v[42:45], v97 offset:29088
	ds_read_b128 v[46:49], v97 offset:29344
	s_waitcnt lgkmcnt(8)
	v_fma_f32 v67, -v32, v84, v67
	v_fma_f32 v68, -v32, v88, v68
	v_fma_f32 v67, -v33, v85, v67
	v_fma_f32 v68, -v33, v89, v68
	v_fma_f32 v67, -v34, v86, v67
	v_fma_f32 v68, -v34, v90, v68
	v_fma_f32 v67, -v35, v87, v67
	v_fma_f32 v68, -v35, v91, v68
	ds_read_b128 v[84:87], v97 offset:29104
	ds_read_b128 v[88:91], v97 offset:29360
	s_waitcnt lgkmcnt(8)
; NI void dn_chunk_local(const P& p, int dh, int n, char* lds) {
;     ...
;       for (int i = hb * 32; i < hb * 32 + 32; ++i) {
;         float a = x[i];
; #pragma unroll
;         for (int j = 0; j < i; ++j) a -= Ls[i * 64 + j] * x[j];
;         x[i] = a;
;         if ((i & 3) == 3) __builtin_amdgcn_sched_barrier(0);
;       }
	v_fma_f32 v67, -v36, v92, v67
	v_fma_f32 v68, -v36, v98, v68
	v_fma_f32 v67, -v37, v93, v67
	v_fma_f32 v68, -v37, v99, v68
	v_fma_f32 v67, -v38, v94, v67
	v_fma_f32 v68, -v38, v100, v68
	v_fma_f32 v67, -v39, v95, v67
	v_fma_f32 v68, -v39, v101, v68
	ds_read_b128 v[92:95], v97 offset:29440
	ds_read_b128 v[98:101], v97 offset:29696
	s_waitcnt lgkmcnt(8)
	v_fma_f32 v67, -v52, v102, v67
	v_fma_f32 v68, -v52, v106, v68
	v_fma_f32 v67, -v53, v103, v67
	v_fma_f32 v68, -v53, v107, v68
	v_fma_f32 v67, -v54, v104, v67
	v_fma_f32 v68, -v54, v108, v68
	v_fma_f32 v67, -v55, v105, v67
	v_fma_f32 v68, -v55, v109, v68
	ds_read_b128 v[102:105], v97 offset:29456
	ds_read_b128 v[106:109], v97 offset:29712
	s_waitcnt lgkmcnt(8)
	v_fma_f32 v67, -v56, v110, v67
	v_fma_f32 v68, -v56, v114, v68
	v_fma_f32 v67, -v57, v111, v67
	v_fma_f32 v68, -v57, v115, v68
	v_fma_f32 v67, -v58, v112, v67
	v_fma_f32 v68, -v58, v116, v68
	v_fma_f32 v67, -v59, v113, v67
	v_fma_f32 v68, -v59, v117, v68
	ds_read_b128 v[110:113], v97 offset:29472
	ds_read_b128 v[114:117], v97 offset:29728
	s_waitcnt lgkmcnt(8)
	v_fma_f32 v67, -v60, v42, v67
	v_fma_f32 v68, -v60, v46, v68
	v_fma_f32 v67, -v61, v43, v67
	v_fma_f32 v68, -v61, v47, v68
	v_fma_f32 v67, -v62, v44, v67
	v_fma_f32 v68, -v62, v48, v68
	v_fma_f32 v67, -v63, v45, v67
	v_fma_f32 v68, -v63, v49, v68
	ds_read_b128 v[42:45], v97 offset:29488
	ds_read_b128 v[46:49], v97 offset:29744
	s_waitcnt lgkmcnt(8)
	v_fma_f32 v67, -v64, v84, v67
	v_fma_f32 v68, -v64, v88, v68
	v_fma_f32 v67, -v65, v85, v67
	v_fma_f32 v68, -v65, v89, v68
	v_fma_f32 v67, -v66, v86, v67
	v_fma_f32 v68, -v66, v90, v68
	v_fma_f32 v68, -v67, v91, v68
	ds_read_b128 v[84:87], v97 offset:29504
	ds_read_b128 v[88:91], v97 offset:29760
	s_waitcnt lgkmcnt(8)
	v_fma_f32 v69, -v8, v92, v69
	v_fma_f32 v70, -v8, v98, v70
	v_fma_f32 v69, -v9, v93, v69
	v_fma_f32 v70, -v9, v99, v70
	v_fma_f32 v69, -v10, v94, v69
	v_fma_f32 v70, -v10, v100, v70
	v_fma_f32 v69, -v11, v95, v69
	v_fma_f32 v70, -v11, v101, v70
	ds_read_b128 v[92:95], v97 offset:29520
	ds_read_b128 v[98:101], v97 offset:29776
	s_waitcnt lgkmcnt(8)
	v_fma_f32 v69, -v12, v102, v69
	v_fma_f32 v70, -v12, v106, v70
	v_fma_f32 v69, -v13, v103, v69
	v_fma_f32 v70, -v13, v107, v70
	v_fma_f32 v69, -v14, v104, v69
	v_fma_f32 v70, -v14, v108, v70
	v_fma_f32 v69, -v15, v105, v69
	v_fma_f32 v70, -v15, v109, v70
	ds_read_b128 v[102:105], v97 offset:29536
	ds_read_b128 v[106:109], v97 offset:29792
	s_waitcnt lgkmcnt(8)
	v_fma_f32 v69, -v16, v110, v69
	v_fma_f32 v70, -v16, v114, v70
	v_fma_f32 v69, -v17, v111, v69
	v_fma_f32 v70, -v17, v115, v70
	v_fma_f32 v69, -v18, v112, v69
	v_fma_f32 v70, -v18, v116, v70
	v_fma_f32 v69, -v19, v113, v69
	v_fma_f32 v70, -v19, v117, v70
	ds_read_b128 v[110:113], v97 offset:29552
	ds_read_b128 v[114:117], v97 offset:29808
	s_waitcnt lgkmcnt(8)
	v_fma_f32 v69, -v20, v42, v69
	v_fma_f32 v70, -v20, v46, v70
	v_fma_f32 v69, -v21, v43, v69
	v_fma_f32 v70, -v21, v47, v70
	v_fma_f32 v69, -v22, v44, v69
	v_fma_f32 v70, -v22, v48, v70
	v_fma_f32 v69, -v23, v45, v69
	v_fma_f32 v70, -v23, v49, v70
	ds_read_b128 v[42:45], v97 offset:29568
	ds_read_b128 v[46:49], v97 offset:29824
	s_waitcnt lgkmcnt(8)
	v_fma_f32 v69, -v24, v84, v69
	v_fma_f32 v70, -v24, v88, v70
	v_fma_f32 v69, -v25, v85, v69
	v_fma_f32 v70, -v25, v89, v70
	v_fma_f32 v69, -v26, v86, v69
	v_fma_f32 v70, -v26, v90, v70
	v_fma_f32 v69, -v27, v87, v69
	v_fma_f32 v70, -v27, v91, v70
	ds_read_b128 v[84:87], v97 offset:29584
	ds_read_b128 v[88:91], v97 offset:29840
	s_waitcnt lgkmcnt(8)
	v_fma_f32 v69, -v28, v92, v69
	v_fma_f32 v70, -v28, v98, v70
	v_fma_f32 v69, -v29, v93, v69
	v_fma_f32 v70, -v29, v99, v70
	v_fma_f32 v69, -v30, v94, v69
	v_fma_f32 v70, -v30, v100, v70
	v_fma_f32 v69, -v31, v95, v69
	v_fma_f32 v70, -v31, v101, v70
	ds_read_b128 v[92:95], v97 offset:29600
	ds_read_b128 v[98:101], v97 offset:29856
	s_waitcnt lgkmcnt(8)
	v_fma_f32 v69, -v32, v102, v69
	v_fma_f32 v70, -v32, v106, v70
	v_fma_f32 v69, -v33, v103, v69
	v_fma_f32 v70, -v33, v107, v70
	v_fma_f32 v69, -v34, v104, v69
	v_fma_f32 v70, -v34, v108, v70
	v_fma_f32 v69, -v35, v105, v69
	v_fma_f32 v70, -v35, v109, v70
	ds_read_b128 v[102:105], v97 offset:29616
	ds_read_b128 v[106:109], v97 offset:29872
	s_waitcnt lgkmcnt(8)
	v_fma_f32 v69, -v36, v110, v69
	v_fma_f32 v70, -v36, v114, v70
	v_fma_f32 v69, -v37, v111, v69
	v_fma_f32 v70, -v37, v115, v70
	v_fma_f32 v69, -v38, v112, v69
	v_fma_f32 v70, -v38, v116, v70
	v_fma_f32 v69, -v39, v113, v69
	v_fma_f32 v70, -v39, v117, v70
	ds_read_b128 v[110:113], v97 offset:29632
	ds_read_b128 v[114:117], v97 offset:29888
	s_waitcnt lgkmcnt(8)
	v_fma_f32 v69, -v52, v42, v69
	v_fma_f32 v70, -v52, v46, v70
	v_fma_f32 v69, -v53, v43, v69
	v_fma_f32 v70, -v53, v47, v70
	v_fma_f32 v69, -v54, v44, v69
	v_fma_f32 v70, -v54, v48, v70
	v_fma_f32 v69, -v55, v45, v69
	v_fma_f32 v70, -v55, v49, v70
	ds_read_b128 v[42:45], v97 offset:29952
	ds_read_b128 v[46:49], v97 offset:30208
	s_waitcnt lgkmcnt(8)
	v_fma_f32 v69, -v56, v84, v69
	v_fma_f32 v70, -v56, v88, v70
	v_fma_f32 v69, -v57, v85, v69
	v_fma_f32 v70, -v57, v89, v70
	v_fma_f32 v69, -v58, v86, v69
	v_fma_f32 v70, -v58, v90, v70
	v_fma_f32 v69, -v59, v87, v69
	v_fma_f32 v70, -v59, v91, v70
	ds_read_b128 v[84:87], v97 offset:29968
	ds_read_b128 v[88:91], v97 offset:30224
	s_waitcnt lgkmcnt(8)
	v_fma_f32 v69, -v60, v92, v69
	v_fma_f32 v70, -v60, v98, v70
	v_fma_f32 v69, -v61, v93, v69
	v_fma_f32 v70, -v61, v99, v70
	v_fma_f32 v69, -v62, v94, v69
	v_fma_f32 v70, -v62, v100, v70
	v_fma_f32 v69, -v63, v95, v69
	v_fma_f32 v70, -v63, v101, v70
	ds_read_b128 v[92:95], v97 offset:29984
	ds_read_b128 v[98:101], v97 offset:30240
	s_waitcnt lgkmcnt(8)
; NI void dn_chunk_local(const P& p, int dh, int n, char* lds) {
;     ...
;       for (int i = hb * 32; i < hb * 32 + 32; ++i) {
;         float a = x[i];
; #pragma unroll
;         for (int j = 0; j < i; ++j) a -= Ls[i * 64 + j] * x[j];
;         x[i] = a;
;         if ((i & 3) == 3) __builtin_amdgcn_sched_barrier(0);
;       }
	v_fma_f32 v69, -v64, v102, v69
	v_fma_f32 v70, -v64, v106, v70
	v_fma_f32 v69, -v65, v103, v69
	v_fma_f32 v70, -v65, v107, v70
	v_fma_f32 v69, -v66, v104, v69
	v_fma_f32 v70, -v66, v108, v70
	v_fma_f32 v69, -v67, v105, v69
	v_fma_f32 v70, -v67, v109, v70
	ds_read_b128 v[102:105], v97 offset:30000
	ds_read_b128 v[106:109], v97 offset:30256
	s_waitcnt lgkmcnt(8)
	v_fma_f32 v69, -v68, v110, v69
	v_fma_f32 v70, -v68, v114, v70
	v_fma_f32 v70, -v69, v115, v70
	ds_read_b128 v[110:113], v97 offset:30016
	ds_read_b128 v[114:117], v97 offset:30272
	s_waitcnt lgkmcnt(8)
	v_fma_f32 v71, -v8, v42, v71
	v_fma_f32 v72, -v8, v46, v72
	v_fma_f32 v71, -v9, v43, v71
	v_fma_f32 v72, -v9, v47, v72
	v_fma_f32 v71, -v10, v44, v71
	v_fma_f32 v72, -v10, v48, v72
	v_fma_f32 v71, -v11, v45, v71
	v_fma_f32 v72, -v11, v49, v72
	ds_read_b128 v[42:45], v97 offset:30032
	ds_read_b128 v[46:49], v97 offset:30288
	s_waitcnt lgkmcnt(8)
	v_fma_f32 v71, -v12, v84, v71
	v_fma_f32 v72, -v12, v88, v72
	v_fma_f32 v71, -v13, v85, v71
	v_fma_f32 v72, -v13, v89, v72
	v_fma_f32 v71, -v14, v86, v71
	v_fma_f32 v72, -v14, v90, v72
	v_fma_f32 v71, -v15, v87, v71
	v_fma_f32 v72, -v15, v91, v72
	ds_read_b128 v[84:87], v97 offset:30048
	ds_read_b128 v[88:91], v97 offset:30304
	s_waitcnt lgkmcnt(8)
	v_fma_f32 v71, -v16, v92, v71
	v_fma_f32 v72, -v16, v98, v72
	v_fma_f32 v71, -v17, v93, v71
	v_fma_f32 v72, -v17, v99, v72
	v_fma_f32 v71, -v18, v94, v71
	v_fma_f32 v72, -v18, v100, v72
	v_fma_f32 v71, -v19, v95, v71
	v_fma_f32 v72, -v19, v101, v72
	ds_read_b128 v[92:95], v97 offset:30064
	ds_read_b128 v[98:101], v97 offset:30320
	s_waitcnt lgkmcnt(8)
	v_fma_f32 v71, -v20, v102, v71
	v_fma_f32 v72, -v20, v106, v72
	v_fma_f32 v71, -v21, v103, v71
	v_fma_f32 v72, -v21, v107, v72
	v_fma_f32 v71, -v22, v104, v71
	v_fma_f32 v72, -v22, v108, v72
	v_fma_f32 v71, -v23, v105, v71
	v_fma_f32 v72, -v23, v109, v72
	ds_read_b128 v[102:105], v97 offset:30080
	ds_read_b128 v[106:109], v97 offset:30336
	s_waitcnt lgkmcnt(8)
	v_fma_f32 v71, -v24, v110, v71
	v_fma_f32 v72, -v24, v114, v72
	v_fma_f32 v71, -v25, v111, v71
	v_fma_f32 v72, -v25, v115, v72
	v_fma_f32 v71, -v26, v112, v71
	v_fma_f32 v72, -v26, v116, v72
	v_fma_f32 v71, -v27, v113, v71
	v_fma_f32 v72, -v27, v117, v72
	ds_read_b128 v[110:113], v97 offset:30096
	ds_read_b128 v[114:117], v97 offset:30352
	s_waitcnt lgkmcnt(8)
	v_fma_f32 v71, -v28, v42, v71
	v_fma_f32 v72, -v28, v46, v72
	v_fma_f32 v71, -v29, v43, v71
	v_fma_f32 v72, -v29, v47, v72
	v_fma_f32 v71, -v30, v44, v71
	v_fma_f32 v72, -v30, v48, v72
	v_fma_f32 v71, -v31, v45, v71
	v_fma_f32 v72, -v31, v49, v72
	ds_read_b128 v[42:45], v97 offset:30112
	ds_read_b128 v[46:49], v97 offset:30368
	s_waitcnt lgkmcnt(8)
	v_fma_f32 v71, -v32, v84, v71
	v_fma_f32 v72, -v32, v88, v72
	v_fma_f32 v71, -v33, v85, v71
	v_fma_f32 v72, -v33, v89, v72
	v_fma_f32 v71, -v34, v86, v71
	v_fma_f32 v72, -v34, v90, v72
	v_fma_f32 v71, -v35, v87, v71
	v_fma_f32 v72, -v35, v91, v72
	ds_read_b128 v[84:87], v97 offset:30128
	ds_read_b128 v[88:91], v97 offset:30384
	s_waitcnt lgkmcnt(8)
	v_fma_f32 v71, -v36, v92, v71
	v_fma_f32 v72, -v36, v98, v72
	v_fma_f32 v71, -v37, v93, v71
	v_fma_f32 v72, -v37, v99, v72
	v_fma_f32 v71, -v38, v94, v71
	v_fma_f32 v72, -v38, v100, v72
	v_fma_f32 v71, -v39, v95, v71
	v_fma_f32 v72, -v39, v101, v72
	ds_read_b128 v[92:95], v97 offset:30144
	ds_read_b128 v[98:101], v97 offset:30400
	s_waitcnt lgkmcnt(8)
	v_fma_f32 v71, -v52, v102, v71
	v_fma_f32 v72, -v52, v106, v72
	v_fma_f32 v71, -v53, v103, v71
	v_fma_f32 v72, -v53, v107, v72
	v_fma_f32 v71, -v54, v104, v71
	v_fma_f32 v72, -v54, v108, v72
	v_fma_f32 v71, -v55, v105, v71
	v_fma_f32 v72, -v55, v109, v72
	ds_read_b128 v[102:105], v97 offset:30464
	ds_read_b128 v[106:109], v97 offset:30720
	s_waitcnt lgkmcnt(8)
	v_fma_f32 v71, -v56, v110, v71
	v_fma_f32 v72, -v56, v114, v72
	v_fma_f32 v71, -v57, v111, v71
	v_fma_f32 v72, -v57, v115, v72
	v_fma_f32 v71, -v58, v112, v71
	v_fma_f32 v72, -v58, v116, v72
	v_fma_f32 v71, -v59, v113, v71
	v_fma_f32 v72, -v59, v117, v72
	ds_read_b128 v[110:113], v97 offset:30480
	ds_read_b128 v[114:117], v97 offset:30736
	s_waitcnt lgkmcnt(8)
	v_fma_f32 v71, -v60, v42, v71
	v_fma_f32 v72, -v60, v46, v72
	v_fma_f32 v71, -v61, v43, v71
	v_fma_f32 v72, -v61, v47, v72
	v_fma_f32 v71, -v62, v44, v71
	v_fma_f32 v72, -v62, v48, v72
	v_fma_f32 v71, -v63, v45, v71
	v_fma_f32 v72, -v63, v49, v72
	ds_read_b128 v[42:45], v97 offset:30496
	ds_read_b128 v[46:49], v97 offset:30752
	s_waitcnt lgkmcnt(8)
	v_fma_f32 v71, -v64, v84, v71
	v_fma_f32 v72, -v64, v88, v72
	v_fma_f32 v71, -v65, v85, v71
	v_fma_f32 v72, -v65, v89, v72
	v_fma_f32 v71, -v66, v86, v71
	v_fma_f32 v72, -v66, v90, v72
	v_fma_f32 v71, -v67, v87, v71
	v_fma_f32 v72, -v67, v91, v72
	ds_read_b128 v[84:87], v97 offset:30512
	ds_read_b128 v[88:91], v97 offset:30768
	s_waitcnt lgkmcnt(8)
	v_fma_f32 v71, -v68, v92, v71
	v_fma_f32 v72, -v68, v98, v72
	v_fma_f32 v71, -v69, v93, v71
	v_fma_f32 v72, -v69, v99, v72
	v_fma_f32 v71, -v70, v94, v71
	v_fma_f32 v72, -v70, v100, v72
	v_fma_f32 v72, -v71, v101, v72
	ds_read_b128 v[92:95], v97 offset:30528
	ds_read_b128 v[98:101], v97 offset:30784
	s_waitcnt lgkmcnt(8)
	v_fma_f32 v73, -v8, v102, v73
	v_fma_f32 v74, -v8, v106, v74
	v_fma_f32 v73, -v9, v103, v73
	v_fma_f32 v74, -v9, v107, v74
	v_fma_f32 v73, -v10, v104, v73
	v_fma_f32 v74, -v10, v108, v74
	v_fma_f32 v73, -v11, v105, v73
	v_fma_f32 v74, -v11, v109, v74
	ds_read_b128 v[102:105], v97 offset:30544
	ds_read_b128 v[106:109], v97 offset:30800
	s_waitcnt lgkmcnt(8)
; NI void dn_chunk_local(const P& p, int dh, int n, char* lds) {
;     ...
;       for (int i = hb * 32; i < hb * 32 + 32; ++i) {
;         float a = x[i];
; #pragma unroll
;         for (int j = 0; j < i; ++j) a -= Ls[i * 64 + j] * x[j];
;         x[i] = a;
;         if ((i & 3) == 3) __builtin_amdgcn_sched_barrier(0);
;       }
	v_fma_f32 v73, -v12, v110, v73
	v_fma_f32 v74, -v12, v114, v74
	v_fma_f32 v73, -v13, v111, v73
	v_fma_f32 v74, -v13, v115, v74
	v_fma_f32 v73, -v14, v112, v73
	v_fma_f32 v74, -v14, v116, v74
	v_fma_f32 v73, -v15, v113, v73
	v_fma_f32 v74, -v15, v117, v74
	ds_read_b128 v[110:113], v97 offset:30560
	ds_read_b128 v[114:117], v97 offset:30816
	s_waitcnt lgkmcnt(8)
	v_fma_f32 v73, -v16, v42, v73
	v_fma_f32 v74, -v16, v46, v74
	v_fma_f32 v73, -v17, v43, v73
	v_fma_f32 v74, -v17, v47, v74
	v_fma_f32 v73, -v18, v44, v73
	v_fma_f32 v74, -v18, v48, v74
	v_fma_f32 v73, -v19, v45, v73
	v_fma_f32 v74, -v19, v49, v74
	ds_read_b128 v[42:45], v97 offset:30576
	ds_read_b128 v[46:49], v97 offset:30832
	s_waitcnt lgkmcnt(8)
	v_fma_f32 v73, -v20, v84, v73
	v_fma_f32 v74, -v20, v88, v74
	v_fma_f32 v73, -v21, v85, v73
	v_fma_f32 v74, -v21, v89, v74
	v_fma_f32 v73, -v22, v86, v73
	v_fma_f32 v74, -v22, v90, v74
	v_fma_f32 v73, -v23, v87, v73
	v_fma_f32 v74, -v23, v91, v74
	ds_read_b128 v[84:87], v97 offset:30592
	ds_read_b128 v[88:91], v97 offset:30848
	s_waitcnt lgkmcnt(8)
	v_fma_f32 v73, -v24, v92, v73
	v_fma_f32 v74, -v24, v98, v74
	v_fma_f32 v73, -v25, v93, v73
	v_fma_f32 v74, -v25, v99, v74
	v_fma_f32 v73, -v26, v94, v73
	v_fma_f32 v74, -v26, v100, v74
	v_fma_f32 v73, -v27, v95, v73
	v_fma_f32 v74, -v27, v101, v74
	ds_read_b128 v[92:95], v97 offset:30608
	ds_read_b128 v[98:101], v97 offset:30864
	s_waitcnt lgkmcnt(8)
	v_fma_f32 v73, -v28, v102, v73
	v_fma_f32 v74, -v28, v106, v74
	v_fma_f32 v73, -v29, v103, v73
	v_fma_f32 v74, -v29, v107, v74
	v_fma_f32 v73, -v30, v104, v73
	v_fma_f32 v74, -v30, v108, v74
	v_fma_f32 v73, -v31, v105, v73
	v_fma_f32 v74, -v31, v109, v74
	ds_read_b128 v[102:105], v97 offset:30624
	ds_read_b128 v[106:109], v97 offset:30880
	s_waitcnt lgkmcnt(8)
	v_fma_f32 v73, -v32, v110, v73
	v_fma_f32 v74, -v32, v114, v74
	v_fma_f32 v73, -v33, v111, v73
	v_fma_f32 v74, -v33, v115, v74
	v_fma_f32 v73, -v34, v112, v73
	v_fma_f32 v74, -v34, v116, v74
	v_fma_f32 v73, -v35, v113, v73
	v_fma_f32 v74, -v35, v117, v74
	ds_read_b128 v[110:113], v97 offset:30640
	ds_read_b128 v[114:117], v97 offset:30896
	s_waitcnt lgkmcnt(8)
	v_fma_f32 v73, -v36, v42, v73
	v_fma_f32 v74, -v36, v46, v74
	v_fma_f32 v73, -v37, v43, v73
	v_fma_f32 v74, -v37, v47, v74
	v_fma_f32 v73, -v38, v44, v73
	v_fma_f32 v74, -v38, v48, v74
	v_fma_f32 v73, -v39, v45, v73
	v_fma_f32 v74, -v39, v49, v74
	ds_read_b128 v[42:45], v97 offset:30656
	ds_read_b128 v[46:49], v97 offset:30912
	s_waitcnt lgkmcnt(8)
	v_fma_f32 v73, -v52, v84, v73
	v_fma_f32 v74, -v52, v88, v74
	v_fma_f32 v73, -v53, v85, v73
	v_fma_f32 v74, -v53, v89, v74
	v_fma_f32 v73, -v54, v86, v73
	v_fma_f32 v74, -v54, v90, v74
	v_fma_f32 v73, -v55, v87, v73
	v_fma_f32 v74, -v55, v91, v74
	ds_read_b128 v[84:87], v97 offset:30672
	ds_read_b128 v[88:91], v97 offset:30928
	s_waitcnt lgkmcnt(8)
	v_fma_f32 v73, -v56, v92, v73
	v_fma_f32 v74, -v56, v98, v74
	v_fma_f32 v73, -v57, v93, v73
	v_fma_f32 v74, -v57, v99, v74
	v_fma_f32 v73, -v58, v94, v73
	v_fma_f32 v74, -v58, v100, v74
	v_fma_f32 v73, -v59, v95, v73
	v_fma_f32 v74, -v59, v101, v74
	ds_read_b128 v[92:95], v97 offset:30976
	ds_read_b128 v[98:101], v97 offset:31232
	s_waitcnt lgkmcnt(8)
	v_fma_f32 v73, -v60, v102, v73
	v_fma_f32 v74, -v60, v106, v74
	v_fma_f32 v73, -v61, v103, v73
	v_fma_f32 v74, -v61, v107, v74
	v_fma_f32 v73, -v62, v104, v73
	v_fma_f32 v74, -v62, v108, v74
	v_fma_f32 v73, -v63, v105, v73
	v_fma_f32 v74, -v63, v109, v74
	ds_read_b128 v[102:105], v97 offset:30992
	ds_read_b128 v[106:109], v97 offset:31248
	s_waitcnt lgkmcnt(8)
	v_fma_f32 v73, -v64, v110, v73
	v_fma_f32 v74, -v64, v114, v74
	v_fma_f32 v73, -v65, v111, v73
	v_fma_f32 v74, -v65, v115, v74
	v_fma_f32 v73, -v66, v112, v73
	v_fma_f32 v74, -v66, v116, v74
	v_fma_f32 v73, -v67, v113, v73
	v_fma_f32 v74, -v67, v117, v74
	ds_read_b128 v[110:113], v97 offset:31008
	ds_read_b128 v[114:117], v97 offset:31264
	s_waitcnt lgkmcnt(8)
	v_fma_f32 v73, -v68, v42, v73
	v_fma_f32 v74, -v68, v46, v74
	v_fma_f32 v73, -v69, v43, v73
	v_fma_f32 v74, -v69, v47, v74
	v_fma_f32 v73, -v70, v44, v73
	v_fma_f32 v74, -v70, v48, v74
	v_fma_f32 v73, -v71, v45, v73
	v_fma_f32 v74, -v71, v49, v74
	ds_read_b128 v[42:45], v97 offset:31024
	ds_read_b128 v[46:49], v97 offset:31280
	s_waitcnt lgkmcnt(8)
	v_fma_f32 v73, -v72, v84, v73
	v_fma_f32 v74, -v72, v88, v74
	v_fma_f32 v74, -v73, v89, v74
	ds_read_b128 v[84:87], v97 offset:31040
	ds_read_b128 v[88:91], v97 offset:31296
	s_waitcnt lgkmcnt(8)
	v_fma_f32 v75, -v8, v92, v75
	v_fma_f32 v76, -v8, v98, v76
	v_fma_f32 v75, -v9, v93, v75
	v_fma_f32 v76, -v9, v99, v76
	v_fma_f32 v75, -v10, v94, v75
	v_fma_f32 v76, -v10, v100, v76
	v_fma_f32 v75, -v11, v95, v75
	v_fma_f32 v76, -v11, v101, v76
	ds_read_b128 v[92:95], v97 offset:31056
	ds_read_b128 v[98:101], v97 offset:31312
	s_waitcnt lgkmcnt(8)
	v_fma_f32 v75, -v12, v102, v75
	v_fma_f32 v76, -v12, v106, v76
	v_fma_f32 v75, -v13, v103, v75
	v_fma_f32 v76, -v13, v107, v76
	v_fma_f32 v75, -v14, v104, v75
	v_fma_f32 v76, -v14, v108, v76
	v_fma_f32 v75, -v15, v105, v75
	v_fma_f32 v76, -v15, v109, v76
	ds_read_b128 v[102:105], v97 offset:31072
	ds_read_b128 v[106:109], v97 offset:31328
	s_waitcnt lgkmcnt(8)
	v_fma_f32 v75, -v16, v110, v75
	v_fma_f32 v76, -v16, v114, v76
	v_fma_f32 v75, -v17, v111, v75
	v_fma_f32 v76, -v17, v115, v76
	v_fma_f32 v75, -v18, v112, v75
	v_fma_f32 v76, -v18, v116, v76
	v_fma_f32 v75, -v19, v113, v75
	v_fma_f32 v76, -v19, v117, v76
	ds_read_b128 v[110:113], v97 offset:31088
	ds_read_b128 v[114:117], v97 offset:31344
	s_waitcnt lgkmcnt(8)
; NI void dn_chunk_local(const P& p, int dh, int n, char* lds) {
;     ...
;       for (int i = hb * 32; i < hb * 32 + 32; ++i) {
;         float a = x[i];
; #pragma unroll
;         for (int j = 0; j < i; ++j) a -= Ls[i * 64 + j] * x[j];
;         x[i] = a;
;         if ((i & 3) == 3) __builtin_amdgcn_sched_barrier(0);
;       }
	v_fma_f32 v75, -v20, v42, v75
	v_fma_f32 v76, -v20, v46, v76
	v_fma_f32 v75, -v21, v43, v75
	v_fma_f32 v76, -v21, v47, v76
	v_fma_f32 v75, -v22, v44, v75
	v_fma_f32 v76, -v22, v48, v76
	v_fma_f32 v75, -v23, v45, v75
	v_fma_f32 v76, -v23, v49, v76
	ds_read_b128 v[42:45], v97 offset:31104
	ds_read_b128 v[46:49], v97 offset:31360
	s_waitcnt lgkmcnt(8)
	v_fma_f32 v75, -v24, v84, v75
	v_fma_f32 v76, -v24, v88, v76
	v_fma_f32 v75, -v25, v85, v75
	v_fma_f32 v76, -v25, v89, v76
	v_fma_f32 v75, -v26, v86, v75
	v_fma_f32 v76, -v26, v90, v76
	v_fma_f32 v75, -v27, v87, v75
	v_fma_f32 v76, -v27, v91, v76
	ds_read_b128 v[84:87], v97 offset:31120
	ds_read_b128 v[88:91], v97 offset:31376
	s_waitcnt lgkmcnt(8)
	v_fma_f32 v75, -v28, v92, v75
	v_fma_f32 v76, -v28, v98, v76
	v_fma_f32 v75, -v29, v93, v75
	v_fma_f32 v76, -v29, v99, v76
	v_fma_f32 v75, -v30, v94, v75
	v_fma_f32 v76, -v30, v100, v76
	v_fma_f32 v75, -v31, v95, v75
	v_fma_f32 v76, -v31, v101, v76
	ds_read_b128 v[92:95], v97 offset:31136
	ds_read_b128 v[98:101], v97 offset:31392
	s_waitcnt lgkmcnt(8)
	v_fma_f32 v75, -v32, v102, v75
	v_fma_f32 v76, -v32, v106, v76
	v_fma_f32 v75, -v33, v103, v75
	v_fma_f32 v76, -v33, v107, v76
	v_fma_f32 v75, -v34, v104, v75
	v_fma_f32 v76, -v34, v108, v76
	v_fma_f32 v75, -v35, v105, v75
	v_fma_f32 v76, -v35, v109, v76
	ds_read_b128 v[102:105], v97 offset:31152
	ds_read_b128 v[106:109], v97 offset:31408
	s_waitcnt lgkmcnt(8)
	v_fma_f32 v75, -v36, v110, v75
	v_fma_f32 v76, -v36, v114, v76
	v_fma_f32 v75, -v37, v111, v75
	v_fma_f32 v76, -v37, v115, v76
	v_fma_f32 v75, -v38, v112, v75
	v_fma_f32 v76, -v38, v116, v76
	v_fma_f32 v75, -v39, v113, v75
	v_fma_f32 v76, -v39, v117, v76
	ds_read_b128 v[110:113], v97 offset:31168
	ds_read_b128 v[114:117], v97 offset:31424
	s_waitcnt lgkmcnt(8)
	v_fma_f32 v75, -v52, v42, v75
	v_fma_f32 v76, -v52, v46, v76
	v_fma_f32 v75, -v53, v43, v75
	v_fma_f32 v76, -v53, v47, v76
	v_fma_f32 v75, -v54, v44, v75
	v_fma_f32 v76, -v54, v48, v76
	v_fma_f32 v75, -v55, v45, v75
	v_fma_f32 v76, -v55, v49, v76
	ds_read_b128 v[42:45], v97 offset:31184
	ds_read_b128 v[46:49], v97 offset:31440
	s_waitcnt lgkmcnt(8)
	v_fma_f32 v75, -v56, v84, v75
	v_fma_f32 v76, -v56, v88, v76
	v_fma_f32 v75, -v57, v85, v75
	v_fma_f32 v76, -v57, v89, v76
	v_fma_f32 v75, -v58, v86, v75
	v_fma_f32 v76, -v58, v90, v76
	v_fma_f32 v75, -v59, v87, v75
	v_fma_f32 v76, -v59, v91, v76
	ds_read_b128 v[84:87], v97 offset:31488
	ds_read_b128 v[88:91], v97 offset:31744
	s_waitcnt lgkmcnt(8)
	v_fma_f32 v75, -v60, v92, v75
	v_fma_f32 v76, -v60, v98, v76
	v_fma_f32 v75, -v61, v93, v75
	v_fma_f32 v76, -v61, v99, v76
	v_fma_f32 v75, -v62, v94, v75
	v_fma_f32 v76, -v62, v100, v76
	v_fma_f32 v75, -v63, v95, v75
	v_fma_f32 v76, -v63, v101, v76
	ds_read_b128 v[92:95], v97 offset:31504
	ds_read_b128 v[98:101], v97 offset:31760
	s_waitcnt lgkmcnt(8)
	v_fma_f32 v75, -v64, v102, v75
	v_fma_f32 v76, -v64, v106, v76
	v_fma_f32 v75, -v65, v103, v75
	v_fma_f32 v76, -v65, v107, v76
	v_fma_f32 v75, -v66, v104, v75
	v_fma_f32 v76, -v66, v108, v76
	v_fma_f32 v75, -v67, v105, v75
	v_fma_f32 v76, -v67, v109, v76
	ds_read_b128 v[102:105], v97 offset:31520
	ds_read_b128 v[106:109], v97 offset:31776
	s_waitcnt lgkmcnt(8)
	v_fma_f32 v75, -v68, v110, v75
	v_fma_f32 v76, -v68, v114, v76
	v_fma_f32 v75, -v69, v111, v75
	v_fma_f32 v76, -v69, v115, v76
	v_fma_f32 v75, -v70, v112, v75
	v_fma_f32 v76, -v70, v116, v76
	v_fma_f32 v75, -v71, v113, v75
	v_fma_f32 v76, -v71, v117, v76
	ds_read_b128 v[110:113], v97 offset:31536
	ds_read_b128 v[114:117], v97 offset:31792
	s_waitcnt lgkmcnt(8)
	v_fma_f32 v75, -v72, v42, v75
	v_fma_f32 v76, -v72, v46, v76
	v_fma_f32 v75, -v73, v43, v75
	v_fma_f32 v76, -v73, v47, v76
	v_fma_f32 v75, -v74, v44, v75
	v_fma_f32 v76, -v74, v48, v76
	v_fma_f32 v76, -v75, v49, v76
	ds_read_b128 v[42:45], v97 offset:31552
	ds_read_b128 v[46:49], v97 offset:31808
	s_waitcnt lgkmcnt(8)
	v_fma_f32 v77, -v8, v84, v77
	v_fma_f32 v78, -v8, v88, v78
	v_fma_f32 v77, -v9, v85, v77
	v_fma_f32 v78, -v9, v89, v78
	v_fma_f32 v77, -v10, v86, v77
	v_fma_f32 v78, -v10, v90, v78
	v_fma_f32 v77, -v11, v87, v77
	v_fma_f32 v78, -v11, v91, v78
	ds_read_b128 v[84:87], v97 offset:31568
	ds_read_b128 v[88:91], v97 offset:31824
	s_waitcnt lgkmcnt(8)
	v_fma_f32 v77, -v12, v92, v77
	v_fma_f32 v78, -v12, v98, v78
	v_fma_f32 v77, -v13, v93, v77
	v_fma_f32 v78, -v13, v99, v78
	v_fma_f32 v77, -v14, v94, v77
	v_fma_f32 v78, -v14, v100, v78
	v_fma_f32 v77, -v15, v95, v77
	v_fma_f32 v78, -v15, v101, v78
	ds_read_b128 v[92:95], v97 offset:31584
	ds_read_b128 v[98:101], v97 offset:31840
	s_waitcnt lgkmcnt(8)
	v_fma_f32 v77, -v16, v102, v77
	v_fma_f32 v78, -v16, v106, v78
	v_fma_f32 v77, -v17, v103, v77
	v_fma_f32 v78, -v17, v107, v78
	v_fma_f32 v77, -v18, v104, v77
	v_fma_f32 v78, -v18, v108, v78
	v_fma_f32 v77, -v19, v105, v77
	v_fma_f32 v78, -v19, v109, v78
	ds_read_b128 v[102:105], v97 offset:31600
	ds_read_b128 v[106:109], v97 offset:31856
	s_waitcnt lgkmcnt(8)
	v_fma_f32 v77, -v20, v110, v77
	v_fma_f32 v78, -v20, v114, v78
	v_fma_f32 v77, -v21, v111, v77
	v_fma_f32 v78, -v21, v115, v78
	v_fma_f32 v77, -v22, v112, v77
	v_fma_f32 v78, -v22, v116, v78
	v_fma_f32 v77, -v23, v113, v77
	v_fma_f32 v78, -v23, v117, v78
	ds_read_b128 v[110:113], v97 offset:31616
	ds_read_b128 v[114:117], v97 offset:31872
	s_waitcnt lgkmcnt(8)
	v_fma_f32 v77, -v24, v42, v77
	v_fma_f32 v78, -v24, v46, v78
	v_fma_f32 v77, -v25, v43, v77
	v_fma_f32 v78, -v25, v47, v78
	v_fma_f32 v77, -v26, v44, v77
	v_fma_f32 v78, -v26, v48, v78
	v_fma_f32 v77, -v27, v45, v77
	v_fma_f32 v78, -v27, v49, v78
	ds_read_b128 v[42:45], v97 offset:31632
	ds_read_b128 v[46:49], v97 offset:31888
	s_waitcnt lgkmcnt(8)
; NI void dn_chunk_local(const P& p, int dh, int n, char* lds) {
;     ...
;       for (int i = hb * 32; i < hb * 32 + 32; ++i) {
;         float a = x[i];
; #pragma unroll
;         for (int j = 0; j < i; ++j) a -= Ls[i * 64 + j] * x[j];
;         x[i] = a;
;         if ((i & 3) == 3) __builtin_amdgcn_sched_barrier(0);
;       }
	v_fma_f32 v77, -v28, v84, v77
	v_fma_f32 v78, -v28, v88, v78
	v_fma_f32 v77, -v29, v85, v77
	v_fma_f32 v78, -v29, v89, v78
	v_fma_f32 v77, -v30, v86, v77
	v_fma_f32 v78, -v30, v90, v78
	v_fma_f32 v77, -v31, v87, v77
	v_fma_f32 v78, -v31, v91, v78
	ds_read_b128 v[84:87], v97 offset:31648
	ds_read_b128 v[88:91], v97 offset:31904
	s_waitcnt lgkmcnt(8)
	v_fma_f32 v77, -v32, v92, v77
	v_fma_f32 v78, -v32, v98, v78
	v_fma_f32 v77, -v33, v93, v77
	v_fma_f32 v78, -v33, v99, v78
	v_fma_f32 v77, -v34, v94, v77
	v_fma_f32 v78, -v34, v100, v78
	v_fma_f32 v77, -v35, v95, v77
	v_fma_f32 v78, -v35, v101, v78
	ds_read_b128 v[92:95], v97 offset:31664
	ds_read_b128 v[98:101], v97 offset:31920
	s_waitcnt lgkmcnt(8)
	v_fma_f32 v77, -v36, v102, v77
	v_fma_f32 v78, -v36, v106, v78
	v_fma_f32 v77, -v37, v103, v77
	v_fma_f32 v78, -v37, v107, v78
	v_fma_f32 v77, -v38, v104, v77
	v_fma_f32 v78, -v38, v108, v78
	v_fma_f32 v77, -v39, v105, v77
	v_fma_f32 v78, -v39, v109, v78
	ds_read_b128 v[102:105], v97 offset:31680
	ds_read_b128 v[106:109], v97 offset:31936
	s_waitcnt lgkmcnt(8)
	v_fma_f32 v77, -v52, v110, v77
	v_fma_f32 v78, -v52, v114, v78
	v_fma_f32 v77, -v53, v111, v77
	v_fma_f32 v78, -v53, v115, v78
	v_fma_f32 v77, -v54, v112, v77
	v_fma_f32 v78, -v54, v116, v78
	v_fma_f32 v77, -v55, v113, v77
	v_fma_f32 v78, -v55, v117, v78
	ds_read_b128 v[110:113], v97 offset:31696
	ds_read_b128 v[114:117], v97 offset:31952
	s_waitcnt lgkmcnt(8)
	v_fma_f32 v77, -v56, v42, v77
	v_fma_f32 v78, -v56, v46, v78
	v_fma_f32 v77, -v57, v43, v77
	v_fma_f32 v78, -v57, v47, v78
	v_fma_f32 v77, -v58, v44, v77
	v_fma_f32 v78, -v58, v48, v78
	v_fma_f32 v77, -v59, v45, v77
	v_fma_f32 v78, -v59, v49, v78
	ds_read_b128 v[42:45], v97 offset:31712
	ds_read_b128 v[46:49], v97 offset:31968
	s_waitcnt lgkmcnt(8)
	v_fma_f32 v77, -v60, v84, v77
	v_fma_f32 v78, -v60, v88, v78
	v_fma_f32 v77, -v61, v85, v77
	v_fma_f32 v78, -v61, v89, v78
	v_fma_f32 v77, -v62, v86, v77
	v_fma_f32 v78, -v62, v90, v78
	v_fma_f32 v77, -v63, v87, v77
	v_fma_f32 v78, -v63, v91, v78
	ds_read_b128 v[84:87], v97 offset:32000
	ds_read_b128 v[88:91], v97 offset:32256
	s_waitcnt lgkmcnt(8)
	v_fma_f32 v77, -v64, v92, v77
	v_fma_f32 v78, -v64, v98, v78
	v_fma_f32 v77, -v65, v93, v77
	v_fma_f32 v78, -v65, v99, v78
	v_fma_f32 v77, -v66, v94, v77
	v_fma_f32 v78, -v66, v100, v78
	v_fma_f32 v77, -v67, v95, v77
	v_fma_f32 v78, -v67, v101, v78
	ds_read_b128 v[92:95], v97 offset:32016
	ds_read_b128 v[98:101], v97 offset:32272
	s_waitcnt lgkmcnt(8)
	v_fma_f32 v77, -v68, v102, v77
	v_fma_f32 v78, -v68, v106, v78
	v_fma_f32 v77, -v69, v103, v77
	v_fma_f32 v78, -v69, v107, v78
	v_fma_f32 v77, -v70, v104, v77
	v_fma_f32 v78, -v70, v108, v78
	v_fma_f32 v77, -v71, v105, v77
	v_fma_f32 v78, -v71, v109, v78
	ds_read_b128 v[102:105], v97 offset:32032
	ds_read_b128 v[106:109], v97 offset:32288
	s_waitcnt lgkmcnt(8)
	v_fma_f32 v77, -v72, v110, v77
	v_fma_f32 v78, -v72, v114, v78
	v_fma_f32 v77, -v73, v111, v77
	v_fma_f32 v78, -v73, v115, v78
	v_fma_f32 v77, -v74, v112, v77
	v_fma_f32 v78, -v74, v116, v78
	v_fma_f32 v77, -v75, v113, v77
	v_fma_f32 v78, -v75, v117, v78
	ds_read_b128 v[110:113], v97 offset:32048
	ds_read_b128 v[114:117], v97 offset:32304
	s_waitcnt lgkmcnt(8)
	v_fma_f32 v77, -v76, v42, v77
	v_fma_f32 v78, -v76, v46, v78
	v_fma_f32 v78, -v77, v47, v78
	ds_read_b128 v[42:45], v97 offset:32064
	ds_read_b128 v[46:49], v97 offset:32320
	s_waitcnt lgkmcnt(8)
	v_fma_f32 v79, -v8, v84, v79
	v_fma_f32 v80, -v8, v88, v80
	v_fma_f32 v79, -v9, v85, v79
	v_fma_f32 v80, -v9, v89, v80
	v_fma_f32 v79, -v10, v86, v79
	v_fma_f32 v80, -v10, v90, v80
	v_fma_f32 v79, -v11, v87, v79
	v_fma_f32 v80, -v11, v91, v80
	ds_read_b128 v[84:87], v97 offset:32080
	ds_read_b128 v[88:91], v97 offset:32336
	s_waitcnt lgkmcnt(8)
	v_fma_f32 v79, -v12, v92, v79
	v_fma_f32 v80, -v12, v98, v80
	v_fma_f32 v79, -v13, v93, v79
	v_fma_f32 v80, -v13, v99, v80
	v_fma_f32 v79, -v14, v94, v79
	v_fma_f32 v80, -v14, v100, v80
	v_fma_f32 v79, -v15, v95, v79
	v_fma_f32 v80, -v15, v101, v80
	ds_read_b128 v[92:95], v97 offset:32096
	ds_read_b128 v[98:101], v97 offset:32352
	s_waitcnt lgkmcnt(8)
	v_fma_f32 v79, -v16, v102, v79
	v_fma_f32 v80, -v16, v106, v80
	v_fma_f32 v79, -v17, v103, v79
	v_fma_f32 v80, -v17, v107, v80
	v_fma_f32 v79, -v18, v104, v79
	v_fma_f32 v80, -v18, v108, v80
	v_fma_f32 v79, -v19, v105, v79
	v_fma_f32 v80, -v19, v109, v80
	ds_read_b128 v[102:105], v97 offset:32112
	ds_read_b128 v[106:109], v97 offset:32368
	s_waitcnt lgkmcnt(8)
	v_fma_f32 v79, -v20, v110, v79
	v_fma_f32 v80, -v20, v114, v80
	v_fma_f32 v79, -v21, v111, v79
	v_fma_f32 v80, -v21, v115, v80
	v_fma_f32 v79, -v22, v112, v79
	v_fma_f32 v80, -v22, v116, v80
	v_fma_f32 v79, -v23, v113, v79
	v_fma_f32 v80, -v23, v117, v80
	ds_read_b128 v[110:113], v97 offset:32128
	ds_read_b128 v[114:117], v97 offset:32384
	s_waitcnt lgkmcnt(8)
	v_fma_f32 v79, -v24, v42, v79
	v_fma_f32 v80, -v24, v46, v80
	v_fma_f32 v79, -v25, v43, v79
	v_fma_f32 v80, -v25, v47, v80
	v_fma_f32 v79, -v26, v44, v79
	v_fma_f32 v80, -v26, v48, v80
	v_fma_f32 v79, -v27, v45, v79
	v_fma_f32 v80, -v27, v49, v80
	ds_read_b128 v[42:45], v97 offset:32144
	ds_read_b128 v[46:49], v97 offset:32400
	s_waitcnt lgkmcnt(8)
	v_fma_f32 v79, -v28, v84, v79
	v_fma_f32 v80, -v28, v88, v80
	v_fma_f32 v79, -v29, v85, v79
	v_fma_f32 v80, -v29, v89, v80
	v_fma_f32 v79, -v30, v86, v79
	v_fma_f32 v80, -v30, v90, v80
	v_fma_f32 v79, -v31, v87, v79
	v_fma_f32 v80, -v31, v91, v80
	ds_read_b128 v[84:87], v97 offset:32160
	ds_read_b128 v[88:91], v97 offset:32416
	s_waitcnt lgkmcnt(8)
; NI void dn_chunk_local(const P& p, int dh, int n, char* lds) {
;     ...
;       for (int i = hb * 32; i < hb * 32 + 32; ++i) {
;         float a = x[i];
; #pragma unroll
;         for (int j = 0; j < i; ++j) a -= Ls[i * 64 + j] * x[j];
;         x[i] = a;
;         if ((i & 3) == 3) __builtin_amdgcn_sched_barrier(0);
;       }
	v_fma_f32 v79, -v32, v92, v79
	v_fma_f32 v80, -v32, v98, v80
	v_fma_f32 v79, -v33, v93, v79
	v_fma_f32 v80, -v33, v99, v80
	v_fma_f32 v79, -v34, v94, v79
	v_fma_f32 v80, -v34, v100, v80
	v_fma_f32 v79, -v35, v95, v79
	v_fma_f32 v80, -v35, v101, v80
	ds_read_b128 v[92:95], v97 offset:32176
	ds_read_b128 v[98:101], v97 offset:32432
	s_waitcnt lgkmcnt(8)
	v_fma_f32 v79, -v36, v102, v79
	v_fma_f32 v80, -v36, v106, v80
	v_fma_f32 v79, -v37, v103, v79
	v_fma_f32 v80, -v37, v107, v80
	v_fma_f32 v79, -v38, v104, v79
	v_fma_f32 v80, -v38, v108, v80
	v_fma_f32 v79, -v39, v105, v79
	v_fma_f32 v80, -v39, v109, v80
	ds_read_b128 v[102:105], v97 offset:32192
	ds_read_b128 v[106:109], v97 offset:32448
	s_waitcnt lgkmcnt(8)
	v_fma_f32 v79, -v52, v110, v79
	v_fma_f32 v80, -v52, v114, v80
	v_fma_f32 v79, -v53, v111, v79
	v_fma_f32 v80, -v53, v115, v80
	v_fma_f32 v79, -v54, v112, v79
	v_fma_f32 v80, -v54, v116, v80
	v_fma_f32 v79, -v55, v113, v79
	v_fma_f32 v80, -v55, v117, v80
	ds_read_b128 v[110:113], v97 offset:32208
	ds_read_b128 v[114:117], v97 offset:32464
	s_waitcnt lgkmcnt(8)
	v_fma_f32 v79, -v56, v42, v79
	v_fma_f32 v80, -v56, v46, v80
	v_fma_f32 v79, -v57, v43, v79
	v_fma_f32 v80, -v57, v47, v80
	v_fma_f32 v79, -v58, v44, v79
	v_fma_f32 v80, -v58, v48, v80
	v_fma_f32 v79, -v59, v45, v79
	v_fma_f32 v80, -v59, v49, v80
	ds_read_b128 v[42:45], v97 offset:32224
	ds_read_b128 v[46:49], v97 offset:32480
	s_waitcnt lgkmcnt(8)
	v_fma_f32 v79, -v60, v84, v79
	v_fma_f32 v80, -v60, v88, v80
	v_fma_f32 v79, -v61, v85, v79
	v_fma_f32 v80, -v61, v89, v80
	v_fma_f32 v79, -v62, v86, v79
	v_fma_f32 v80, -v62, v90, v80
	v_fma_f32 v79, -v63, v87, v79
	v_fma_f32 v80, -v63, v91, v80
	ds_read_b128 v[84:87], v97 offset:32512
	ds_read_b128 v[88:91], v97 offset:32768
	s_waitcnt lgkmcnt(8)
	v_fma_f32 v79, -v64, v92, v79
	v_fma_f32 v80, -v64, v98, v80
	v_fma_f32 v79, -v65, v93, v79
	v_fma_f32 v80, -v65, v99, v80
	v_fma_f32 v79, -v66, v94, v79
	v_fma_f32 v80, -v66, v100, v80
	v_fma_f32 v79, -v67, v95, v79
	v_fma_f32 v80, -v67, v101, v80
	ds_read_b128 v[92:95], v97 offset:32528
	ds_read_b128 v[98:101], v97 offset:32784
	s_waitcnt lgkmcnt(8)
	v_fma_f32 v79, -v68, v102, v79
	v_fma_f32 v80, -v68, v106, v80
	v_fma_f32 v79, -v69, v103, v79
	v_fma_f32 v80, -v69, v107, v80
	v_fma_f32 v79, -v70, v104, v79
	v_fma_f32 v80, -v70, v108, v80
	v_fma_f32 v79, -v71, v105, v79
	v_fma_f32 v80, -v71, v109, v80
	ds_read_b128 v[102:105], v97 offset:32544
	ds_read_b128 v[106:109], v97 offset:32800
	s_waitcnt lgkmcnt(8)
	v_fma_f32 v79, -v72, v110, v79
	v_fma_f32 v80, -v72, v114, v80
	v_fma_f32 v79, -v73, v111, v79
	v_fma_f32 v80, -v73, v115, v80
	v_fma_f32 v79, -v74, v112, v79
	v_fma_f32 v80, -v74, v116, v80
	v_fma_f32 v79, -v75, v113, v79
	v_fma_f32 v80, -v75, v117, v80
	ds_read_b128 v[110:113], v97 offset:32560
	ds_read_b128 v[114:117], v97 offset:32816
	s_waitcnt lgkmcnt(8)
	v_fma_f32 v79, -v76, v42, v79
	v_fma_f32 v80, -v76, v46, v80
	v_fma_f32 v79, -v77, v43, v79
	v_fma_f32 v80, -v77, v47, v80
	v_fma_f32 v79, -v78, v44, v79
	v_fma_f32 v80, -v78, v48, v80
	v_fma_f32 v80, -v79, v49, v80
	ds_read_b128 v[42:45], v97 offset:32576
	ds_read_b128 v[46:49], v97 offset:32832
	s_waitcnt lgkmcnt(8)
	v_fma_f32 v81, -v8, v84, v81
	v_fma_f32 v82, -v8, v88, v82
	v_fma_f32 v81, -v9, v85, v81
	v_fma_f32 v82, -v9, v89, v82
	v_fma_f32 v81, -v10, v86, v81
	v_fma_f32 v82, -v10, v90, v82
	v_fma_f32 v81, -v11, v87, v81
	v_fma_f32 v82, -v11, v91, v82
	ds_read_b128 v[84:87], v97 offset:32592
	ds_read_b128 v[88:91], v97 offset:32848
	s_waitcnt lgkmcnt(8)
	v_fma_f32 v81, -v12, v92, v81
	v_fma_f32 v82, -v12, v98, v82
	v_fma_f32 v81, -v13, v93, v81
	v_fma_f32 v82, -v13, v99, v82
	v_fma_f32 v81, -v14, v94, v81
	v_fma_f32 v82, -v14, v100, v82
	v_fma_f32 v81, -v15, v95, v81
	v_fma_f32 v82, -v15, v101, v82
	ds_read_b128 v[92:95], v97 offset:32608
	ds_read_b128 v[98:101], v97 offset:32864
	s_waitcnt lgkmcnt(8)
	v_fma_f32 v81, -v16, v102, v81
	v_fma_f32 v82, -v16, v106, v82
	v_fma_f32 v81, -v17, v103, v81
	v_fma_f32 v82, -v17, v107, v82
	v_fma_f32 v81, -v18, v104, v81
	v_fma_f32 v82, -v18, v108, v82
	v_fma_f32 v81, -v19, v105, v81
	v_fma_f32 v82, -v19, v109, v82
	ds_read_b128 v[102:105], v97 offset:32624
	ds_read_b128 v[106:109], v97 offset:32880
	s_waitcnt lgkmcnt(8)
	v_fma_f32 v81, -v20, v110, v81
	v_fma_f32 v82, -v20, v114, v82
	v_fma_f32 v81, -v21, v111, v81
	v_fma_f32 v82, -v21, v115, v82
	v_fma_f32 v81, -v22, v112, v81
	v_fma_f32 v82, -v22, v116, v82
	v_fma_f32 v81, -v23, v113, v81
	v_fma_f32 v82, -v23, v117, v82
	ds_read_b128 v[110:113], v97 offset:32640
	ds_read_b128 v[114:117], v97 offset:32896
	s_waitcnt lgkmcnt(8)
	v_fma_f32 v81, -v24, v42, v81
	v_fma_f32 v82, -v24, v46, v82
	v_fma_f32 v81, -v25, v43, v81
	v_fma_f32 v82, -v25, v47, v82
	v_fma_f32 v81, -v26, v44, v81
	v_fma_f32 v82, -v26, v48, v82
	v_fma_f32 v81, -v27, v45, v81
	v_fma_f32 v82, -v27, v49, v82
	ds_read_b128 v[42:45], v97 offset:32656
	ds_read_b128 v[46:49], v97 offset:32912
	s_waitcnt lgkmcnt(8)
	v_fma_f32 v81, -v28, v84, v81
	v_fma_f32 v82, -v28, v88, v82
	v_fma_f32 v81, -v29, v85, v81
	v_fma_f32 v82, -v29, v89, v82
	v_fma_f32 v81, -v30, v86, v81
	v_fma_f32 v82, -v30, v90, v82
	v_fma_f32 v81, -v31, v87, v81
	v_fma_f32 v82, -v31, v91, v82
	ds_read_b128 v[84:87], v97 offset:32672
	ds_read_b128 v[88:91], v97 offset:32928
	s_waitcnt lgkmcnt(8)
	v_fma_f32 v81, -v32, v92, v81
	v_fma_f32 v82, -v32, v98, v82
	v_fma_f32 v81, -v33, v93, v81
	v_fma_f32 v82, -v33, v99, v82
	v_fma_f32 v81, -v34, v94, v81
	v_fma_f32 v82, -v34, v100, v82
	v_fma_f32 v81, -v35, v95, v81
	v_fma_f32 v82, -v35, v101, v82
	ds_read_b128 v[92:95], v97 offset:32688
	ds_read_b128 v[98:101], v97 offset:32944
	s_waitcnt lgkmcnt(8)
; NI void dn_chunk_local(const P& p, int dh, int n, char* lds) {
;     ...
;       for (int i = hb * 32; i < hb * 32 + 32; ++i) {
;         float a = x[i];
; #pragma unroll
;         for (int j = 0; j < i; ++j) a -= Ls[i * 64 + j] * x[j];
;         x[i] = a;
;         if ((i & 3) == 3) __builtin_amdgcn_sched_barrier(0);
;       }
;     ...
;     if (col < 128) {
;       uint4* dst = (uint4*)((bf16_t*)(ws + WS_DU) + ((size_t)(dh * NCH + n) * 128 + col) * 64);
	v_fma_f32 v81, -v36, v102, v81
	v_fma_f32 v82, -v36, v106, v82
	v_fma_f32 v81, -v37, v103, v81
	v_fma_f32 v82, -v37, v107, v82
	v_fma_f32 v81, -v38, v104, v81
	v_fma_f32 v82, -v38, v108, v82
	v_fma_f32 v81, -v39, v105, v81
	v_fma_f32 v82, -v39, v109, v82
	ds_read_b128 v[102:105], v97 offset:32704
	ds_read_b128 v[106:109], v97 offset:32960
	s_waitcnt lgkmcnt(8)
	v_fma_f32 v81, -v52, v110, v81
	v_fma_f32 v82, -v52, v114, v82
	v_fma_f32 v81, -v53, v111, v81
	v_fma_f32 v82, -v53, v115, v82
	v_fma_f32 v81, -v54, v112, v81
	v_fma_f32 v82, -v54, v116, v82
	v_fma_f32 v81, -v55, v113, v81
	v_fma_f32 v82, -v55, v117, v82
	ds_read_b128 v[110:113], v97 offset:32720
	ds_read_b128 v[114:117], v97 offset:32976
	s_waitcnt lgkmcnt(8)
	v_fma_f32 v81, -v56, v42, v81
	v_fma_f32 v82, -v56, v46, v82
	v_fma_f32 v81, -v57, v43, v81
	v_fma_f32 v82, -v57, v47, v82
	v_fma_f32 v81, -v58, v44, v81
	v_fma_f32 v82, -v58, v48, v82
	v_fma_f32 v81, -v59, v45, v81
	v_fma_f32 v82, -v59, v49, v82
	ds_read_b128 v[42:45], v97 offset:32736
	ds_read_b128 v[46:49], v97 offset:32992
	s_waitcnt lgkmcnt(8)
	v_fma_f32 v81, -v60, v84, v81
	v_fma_f32 v82, -v60, v88, v82
	v_fma_f32 v81, -v61, v85, v81
	v_fma_f32 v82, -v61, v89, v82
	v_fma_f32 v81, -v62, v86, v81
	v_fma_f32 v82, -v62, v90, v82
	v_fma_f32 v81, -v63, v87, v81
	v_fma_f32 v82, -v63, v91, v82
	ds_read_b128 v[84:87], v97 offset:32752
	ds_read_b128 v[88:91], v97 offset:33008
	s_waitcnt lgkmcnt(8)
	v_fma_f32 v81, -v64, v92, v81
	v_fma_f32 v82, -v64, v98, v82
	v_fma_f32 v81, -v65, v93, v81
	v_fma_f32 v82, -v65, v99, v82
	v_fma_f32 v81, -v66, v94, v81
	v_fma_f32 v82, -v66, v100, v82
	v_fma_f32 v81, -v67, v95, v81
	v_fma_f32 v82, -v67, v101, v82
	ds_read_b128 v[92:95], v97 offset:33024
	ds_read_b128 v[98:101], v97 offset:33040
	s_waitcnt lgkmcnt(8)
	v_fma_f32 v81, -v68, v102, v81
	v_fma_f32 v82, -v68, v106, v82
	v_fma_f32 v81, -v69, v103, v81
	v_fma_f32 v82, -v69, v107, v82
	v_fma_f32 v81, -v70, v104, v81
	v_fma_f32 v82, -v70, v108, v82
	v_fma_f32 v81, -v71, v105, v81
	v_fma_f32 v82, -v71, v109, v82
	ds_read_b128 v[102:105], v97 offset:33056
	ds_read_b128 v[106:109], v97 offset:33072
	s_waitcnt lgkmcnt(8)
	v_fma_f32 v81, -v72, v110, v81
	v_fma_f32 v82, -v72, v114, v82
	v_fma_f32 v81, -v73, v111, v81
	v_fma_f32 v82, -v73, v115, v82
	v_fma_f32 v81, -v74, v112, v81
	v_fma_f32 v82, -v74, v116, v82
	v_fma_f32 v81, -v75, v113, v81
	v_fma_f32 v82, -v75, v117, v82
	ds_read_b128 v[110:113], v97 offset:33088
	ds_read_b128 v[114:117], v97 offset:33104
	s_waitcnt lgkmcnt(8)
	v_fma_f32 v81, -v76, v42, v81
	v_fma_f32 v82, -v76, v46, v82
	v_fma_f32 v81, -v77, v43, v81
	v_fma_f32 v82, -v77, v47, v82
	v_fma_f32 v81, -v78, v44, v81
	v_fma_f32 v82, -v78, v48, v82
	v_fma_f32 v81, -v79, v45, v81
	v_fma_f32 v82, -v79, v49, v82
	ds_read_b128 v[42:45], v97 offset:33120
	ds_read_b128 v[46:49], v97 offset:33136
	s_waitcnt lgkmcnt(8)
	v_fma_f32 v81, -v80, v84, v81
	v_fma_f32 v82, -v80, v88, v82
	v_fma_f32 v82, -v81, v89, v82
	ds_read_b128 v[84:87], v97 offset:33152
	ds_read_b128 v[88:91], v97 offset:33168
	s_waitcnt lgkmcnt(9)
	v_fma_f32 v83, -v8, v92, v83
	v_fma_f32 v83, -v9, v93, v83
	v_fma_f32 v83, -v10, v94, v83
	v_fma_f32 v83, -v11, v95, v83
	ds_read_b128 v[92:95], v97 offset:33184
	s_waitcnt lgkmcnt(9)
	v_fma_f32 v83, -v12, v98, v83
	v_fma_f32 v83, -v13, v99, v83
	v_fma_f32 v83, -v14, v100, v83
	v_fma_f32 v83, -v15, v101, v83
	ds_read_b128 v[98:101], v97 offset:33200
	s_waitcnt lgkmcnt(9)
	v_fma_f32 v83, -v16, v102, v83
	v_fma_f32 v83, -v17, v103, v83
	v_fma_f32 v83, -v18, v104, v83
	v_fma_f32 v83, -v19, v105, v83
	ds_read_b128 v[102:105], v97 offset:33216
	s_waitcnt lgkmcnt(9)
	v_fma_f32 v83, -v20, v106, v83
	v_fma_f32 v83, -v21, v107, v83
	v_fma_f32 v83, -v22, v108, v83
	v_fma_f32 v83, -v23, v109, v83
	ds_read_b128 v[106:109], v97 offset:33232
	s_waitcnt lgkmcnt(9)
	v_fma_f32 v83, -v24, v110, v83
	v_fma_f32 v83, -v25, v111, v83
	v_fma_f32 v83, -v26, v112, v83
	v_fma_f32 v83, -v27, v113, v83
	ds_read_b128 v[110:113], v97 offset:33248
	s_waitcnt lgkmcnt(9)
	v_fma_f32 v83, -v28, v114, v83
	v_fma_f32 v83, -v29, v115, v83
	v_fma_f32 v83, -v30, v116, v83
	v_fma_f32 v83, -v31, v117, v83
	ds_read_b128 v[114:117], v97 offset:33264
	s_waitcnt lgkmcnt(9)
	v_fma_f32 v83, -v32, v42, v83
	v_fma_f32 v83, -v33, v43, v83
	v_fma_f32 v83, -v34, v44, v83
	v_fma_f32 v83, -v35, v45, v83
	s_waitcnt lgkmcnt(8)
	v_fma_f32 v83, -v36, v46, v83
	v_fma_f32 v83, -v37, v47, v83
	v_fma_f32 v83, -v38, v48, v83
	v_fma_f32 v83, -v39, v49, v83
	s_waitcnt lgkmcnt(7)
	v_fma_f32 v83, -v52, v84, v83
	v_fma_f32 v83, -v53, v85, v83
	v_fma_f32 v83, -v54, v86, v83
	v_fma_f32 v83, -v55, v87, v83
	s_waitcnt lgkmcnt(6)
	v_fma_f32 v83, -v56, v88, v83
	v_fma_f32 v83, -v57, v89, v83
	v_fma_f32 v83, -v58, v90, v83
	v_fma_f32 v83, -v59, v91, v83
	s_waitcnt lgkmcnt(5)
	v_fma_f32 v83, -v60, v92, v83
	v_fma_f32 v83, -v61, v93, v83
	v_fma_f32 v83, -v62, v94, v83
	v_fma_f32 v83, -v63, v95, v83
	s_waitcnt lgkmcnt(4)
	v_fma_f32 v83, -v64, v98, v83
	v_fma_f32 v83, -v65, v99, v83
	v_fma_f32 v83, -v66, v100, v83
	v_fma_f32 v83, -v67, v101, v83
	s_waitcnt lgkmcnt(3)
	v_fma_f32 v83, -v68, v102, v83
	v_fma_f32 v83, -v69, v103, v83
	v_fma_f32 v83, -v70, v104, v83
	v_fma_f32 v83, -v71, v105, v83
	s_waitcnt lgkmcnt(2)
	v_fma_f32 v83, -v72, v106, v83
	v_fma_f32 v83, -v73, v107, v83
	v_fma_f32 v83, -v74, v108, v83
	v_fma_f32 v83, -v75, v109, v83
	s_waitcnt lgkmcnt(1)
	v_fma_f32 v83, -v76, v110, v83
	v_fma_f32 v83, -v77, v111, v83
	v_fma_f32 v83, -v78, v112, v83
	v_fma_f32 v83, -v79, v113, v83
	s_waitcnt lgkmcnt(0)
	v_fma_f32 v83, -v80, v114, v83
	v_fma_f32 v83, -v81, v115, v83
	v_fma_f32 v83, -v82, v116, v83
	s_mov_b64 s[28:29], exec
	s_mul_i32 s16, s0, 0x2100
	s_add_i32 s16, s16, s27
	s_mov_b32 s17, 0
	s_lshl_b64 s[16:17], s[16:17], 8
	s_and_b64 exec, s[28:29], s[22:23]
	s_cbranch_execz .Ldn_wstore
; DI unsigned pk2(float lo, float hi) { return (unsigned)f2bf(lo) | ((unsigned)f2bf(hi) << 16); }
; NI void dn_chunk_local(const P& p, int dh, int n, char* lds) {
;     ...
;     if (col < 128) {
;       uint4* dst = (uint4*)((bf16_t*)(ws + WS_DU) + ((size_t)(dh * NCH + n) * 128 + col) * 64);
; #pragma unroll
;       for (int i = 0; i < 8; ++i) dst[i] = make_uint4(pk2(x[8 * i], x[8 * i + 1]), pk2(x[8 * i + 2], x[8 * i + 3]), pk2(x[8 * i + 4], x[8 * i + 5]), pk2(x[8 * i + 6], x[8 * i + 7]));
	s_lshl_b64 s[36:37], s[80:81], 14
	v_readlane_b32 s1, v253, 6
	v_lshlrev_b32_e32 v118, 7, v4
	s_add_u32 s36, s1, s36
	v_readlane_b32 s1, v253, 7
	v_mov_b32_e32 v119, 0
	s_addc_u32 s37, s1, s37
	s_nop 0
	v_lshl_add_u64 v[118:119], s[36:37], 0, v[118:119]
	v_cvt_pk_bf16_f32 v84, v8, v9
	v_cvt_pk_bf16_f32 v85, v10, v11
	v_cvt_pk_bf16_f32 v86, v12, v13
	v_cvt_pk_bf16_f32 v87, v14, v15
	s_nop 0
	global_store_dwordx4 v[118:119], v[84:87], off offset:0
	v_cvt_pk_bf16_f32 v88, v16, v17
	v_cvt_pk_bf16_f32 v89, v18, v19
	v_cvt_pk_bf16_f32 v90, v20, v21
	v_cvt_pk_bf16_f32 v91, v22, v23
	s_nop 0
	global_store_dwordx4 v[118:119], v[88:91], off offset:16
	v_cvt_pk_bf16_f32 v92, v24, v25
	v_cvt_pk_bf16_f32 v93, v26, v27
	v_cvt_pk_bf16_f32 v94, v28, v29
	v_cvt_pk_bf16_f32 v95, v30, v31
	s_nop 0
	global_store_dwordx4 v[118:119], v[92:95], off offset:32
	v_cvt_pk_bf16_f32 v98, v32, v33
	v_cvt_pk_bf16_f32 v99, v34, v35
	v_cvt_pk_bf16_f32 v100, v36, v37
	v_cvt_pk_bf16_f32 v101, v38, v39
	s_nop 0
	global_store_dwordx4 v[118:119], v[98:101], off offset:48
	v_cvt_pk_bf16_f32 v102, v52, v53
	v_cvt_pk_bf16_f32 v103, v54, v55
	v_cvt_pk_bf16_f32 v104, v56, v57
	v_cvt_pk_bf16_f32 v105, v58, v59
	s_nop 0
	global_store_dwordx4 v[118:119], v[102:105], off offset:64
	v_cvt_pk_bf16_f32 v106, v60, v61
	v_cvt_pk_bf16_f32 v107, v62, v63
	v_cvt_pk_bf16_f32 v108, v64, v65
	v_cvt_pk_bf16_f32 v109, v66, v67
	s_nop 0
	global_store_dwordx4 v[118:119], v[106:109], off offset:80
	v_cvt_pk_bf16_f32 v110, v68, v69
	v_cvt_pk_bf16_f32 v111, v70, v71
	v_cvt_pk_bf16_f32 v112, v72, v73
	v_cvt_pk_bf16_f32 v113, v74, v75
	s_nop 0
	global_store_dwordx4 v[118:119], v[110:113], off offset:96
	v_cvt_pk_bf16_f32 v114, v76, v77
	v_cvt_pk_bf16_f32 v115, v78, v79
	v_cvt_pk_bf16_f32 v116, v80, v81
	v_cvt_pk_bf16_f32 v117, v82, v83
	s_nop 0
	global_store_dwordx4 v[118:119], v[114:117], off offset:112
; DI bf16_t f2bf(float x) { unsigned u = __float_as_uint(x); u += 0x7fffu + ((u >> 16) & 1u); return (bf16_t)(u >> 16); }
; DI unsigned pk2(float lo, float hi) { return (unsigned)f2bf(lo) | ((unsigned)f2bf(hi) << 16); }
; NI void dn_chunk_local(const P& p, int dh, int n, char* lds) {
;     ...
;     if (col < 128) {
;       uint4* dst = (uint4*)((bf16_t*)(ws + WS_DU) + ((size_t)(dh * NCH + n) * 128 + col) * 64);
; #pragma unroll
;       for (int i = 0; i < 8; ++i) dst[i] = make_uint4(pk2(x[8 * i], x[8 * i + 1]), pk2(x[8 * i + 2], x[8 * i + 3]), pk2(x[8 * i + 4], x[8 * i + 5]), pk2(x[8 * i + 6], x[8 * i + 7]));
;     } else {
;       bf16_t* dst = (bf16_t*)(ws + WS_DW) + ((size_t)dh * T + n * 64) * 128 + (col - 128);
; #pragma unroll
;       for (int i = 0; i < 64; ++i) dst[(size_t)i * 128] = f2bf(x[i]);
;     }
.Ldn_wstore:
	s_andn2_b64 exec, s[28:29], s[22:23]
	s_cbranch_execz .Ldn_done
	s_add_u32 s36, s94, s16
	s_addc_u32 s37, s95, s17
	s_add_u32 s36, s36, 0x25661f00
	s_addc_u32 s37, s37, 0
	v_lshlrev_b32_e32 v118, 1, v4
	v_mov_b32_e32 v119, 0
	v_lshl_add_u64 v[118:119], s[36:37], 0, v[118:119]
	s_mov_b64 s[36:37], 0x1000
	v_cvt_pk_bf16_f32 v84, v8, v9
	s_nop 0
	global_store_short v[118:119], v84, off offset:0
	global_store_short_d16_hi v[118:119], v84, off offset:256
	v_cvt_pk_bf16_f32 v88, v10, v11
	s_nop 0
	global_store_short v[118:119], v88, off offset:512
	global_store_short_d16_hi v[118:119], v88, off offset:768
	v_cvt_pk_bf16_f32 v92, v12, v13
	s_nop 0
	global_store_short v[118:119], v92, off offset:1024
	global_store_short_d16_hi v[118:119], v92, off offset:1280
	v_cvt_pk_bf16_f32 v98, v14, v15
	s_nop 0
	global_store_short v[118:119], v98, off offset:1536
	global_store_short_d16_hi v[118:119], v98, off offset:1792
	v_cvt_pk_bf16_f32 v102, v16, v17
	s_nop 0
	global_store_short v[118:119], v102, off offset:2048
	global_store_short_d16_hi v[118:119], v102, off offset:2304
	v_cvt_pk_bf16_f32 v106, v18, v19
	s_nop 0
	global_store_short v[118:119], v106, off offset:2560
	global_store_short_d16_hi v[118:119], v106, off offset:2816
	v_cvt_pk_bf16_f32 v110, v20, v21
	s_nop 0
	global_store_short v[118:119], v110, off offset:3072
	global_store_short_d16_hi v[118:119], v110, off offset:3328
	v_cvt_pk_bf16_f32 v114, v22, v23
	s_nop 0
	global_store_short v[118:119], v114, off offset:3584
	global_store_short_d16_hi v[118:119], v114, off offset:3840
	v_lshl_add_u64 v[118:119], v[118:119], 0, s[36:37]
	v_cvt_pk_bf16_f32 v42, v24, v25
	s_nop 0
	global_store_short v[118:119], v42, off offset:0
	global_store_short_d16_hi v[118:119], v42, off offset:256
	v_cvt_pk_bf16_f32 v46, v26, v27
	s_nop 0
	global_store_short v[118:119], v46, off offset:512
	global_store_short_d16_hi v[118:119], v46, off offset:768
	v_cvt_pk_bf16_f32 v84, v28, v29
	s_nop 0
	global_store_short v[118:119], v84, off offset:1024
	global_store_short_d16_hi v[118:119], v84, off offset:1280
	v_cvt_pk_bf16_f32 v88, v30, v31
	s_nop 0
	global_store_short v[118:119], v88, off offset:1536
	global_store_short_d16_hi v[118:119], v88, off offset:1792
	v_cvt_pk_bf16_f32 v92, v32, v33
	s_nop 0
	global_store_short v[118:119], v92, off offset:2048
	global_store_short_d16_hi v[118:119], v92, off offset:2304
	v_cvt_pk_bf16_f32 v98, v34, v35
	s_nop 0
	global_store_short v[118:119], v98, off offset:2560
	global_store_short_d16_hi v[118:119], v98, off offset:2816
	v_cvt_pk_bf16_f32 v102, v36, v37
	s_nop 0
	global_store_short v[118:119], v102, off offset:3072
	global_store_short_d16_hi v[118:119], v102, off offset:3328
	v_cvt_pk_bf16_f32 v106, v38, v39
	s_nop 0
	global_store_short v[118:119], v106, off offset:3584
	global_store_short_d16_hi v[118:119], v106, off offset:3840
	v_lshl_add_u64 v[118:119], v[118:119], 0, s[36:37]
	v_cvt_pk_bf16_f32 v110, v52, v53
	s_nop 0
	global_store_short v[118:119], v110, off offset:0
	global_store_short_d16_hi v[118:119], v110, off offset:256
	v_cvt_pk_bf16_f32 v114, v54, v55
	s_nop 0
	global_store_short v[118:119], v114, off offset:512
	global_store_short_d16_hi v[118:119], v114, off offset:768
	v_cvt_pk_bf16_f32 v42, v56, v57
	s_nop 0
	global_store_short v[118:119], v42, off offset:1024
	global_store_short_d16_hi v[118:119], v42, off offset:1280
	v_cvt_pk_bf16_f32 v46, v58, v59
	s_nop 0
	global_store_short v[118:119], v46, off offset:1536
	global_store_short_d16_hi v[118:119], v46, off offset:1792
	v_cvt_pk_bf16_f32 v84, v60, v61
	s_nop 0
	global_store_short v[118:119], v84, off offset:2048
	global_store_short_d16_hi v[118:119], v84, off offset:2304
	v_cvt_pk_bf16_f32 v88, v62, v63
	s_nop 0
	global_store_short v[118:119], v88, off offset:2560
	global_store_short_d16_hi v[118:119], v88, off offset:2816
	v_cvt_pk_bf16_f32 v92, v64, v65
	s_nop 0
	global_store_short v[118:119], v92, off offset:3072
	global_store_short_d16_hi v[118:119], v92, off offset:3328
	v_cvt_pk_bf16_f32 v98, v66, v67
	s_nop 0
	global_store_short v[118:119], v98, off offset:3584
	global_store_short_d16_hi v[118:119], v98, off offset:3840
	v_lshl_add_u64 v[118:119], v[118:119], 0, s[36:37]
	v_cvt_pk_bf16_f32 v102, v68, v69
	s_nop 0
	global_store_short v[118:119], v102, off offset:0
	global_store_short_d16_hi v[118:119], v102, off offset:256
	v_cvt_pk_bf16_f32 v106, v70, v71
	s_nop 0
	global_store_short v[118:119], v106, off offset:512
	global_store_short_d16_hi v[118:119], v106, off offset:768
	v_cvt_pk_bf16_f32 v110, v72, v73
	s_nop 0
	global_store_short v[118:119], v110, off offset:1024
	global_store_short_d16_hi v[118:119], v110, off offset:1280
	v_cvt_pk_bf16_f32 v114, v74, v75
	s_nop 0
	global_store_short v[118:119], v114, off offset:1536
	global_store_short_d16_hi v[118:119], v114, off offset:1792
	v_cvt_pk_bf16_f32 v42, v76, v77
	s_nop 0
	global_store_short v[118:119], v42, off offset:2048
	global_store_short_d16_hi v[118:119], v42, off offset:2304
	v_cvt_pk_bf16_f32 v46, v78, v79
	s_nop 0
	global_store_short v[118:119], v46, off offset:2560
	global_store_short_d16_hi v[118:119], v46, off offset:2816
	v_cvt_pk_bf16_f32 v84, v80, v81
	s_nop 0
	global_store_short v[118:119], v84, off offset:3072
	global_store_short_d16_hi v[118:119], v84, off offset:3328
	v_cvt_pk_bf16_f32 v88, v82, v83
	s_nop 0
	global_store_short v[118:119], v88, off offset:3584
	global_store_short_d16_hi v[118:119], v88, off offset:3840
.Ldn_done:
	s_mov_b64 exec, s[28:29]
	s_mov_b64 s[22:23], exec
	s_ashr_i32 s1, s0, 31
	v_mov_b64_e32 v[6:7], s[16:17]
	v_mov_b64_e32 v[0:1], s[0:1]
